# NA: local V^T band staged once per round in LDS (full-line loads, ds_read2_b64 operands) instead of 64 scattered 8-byte global loads per lane; plus GLA og unpack deferred
# speedup vs baseline: 1.0509x; 1.0306x over previous
; template <int MODE> ...
;     ...
;             if (MODE == 0) {
;                 const int dr = rs + (kb >> 1) - r + 7;
; #pragma unroll
;                 for (int j = 0; j < 4; ++j) { const int kcol = kc0 + (kb & 1) * 16 + fq * 4 + j; const bool valid = (kcol >= cs) && (kcol < cs + 16);
;                     const int dc = min(max(kcol - qcol + 15, 0), 30);
;                     acc[j] = valid ? acc[j] + rpbL[(h * 15 + dr) * 31 + dc] : -1e30f; }
; template <bool CTXLDS>
; __device__ __forceinline__ void na_tile(const bf16_t* U, const bf16_t* VT, bf16_t* MIX, const float* rpbL, const bf16_t* Kc, const bf16_t* Vc, bool lat, int b, int r, int c0, int qrow0, int h, int lane) {
;     const int fr = lane & 15, fq = lane >> 4;
;     const bf16_t* qp = U + (size_t)(qrow0 + fr) * INP + NQ0 + h * 64 + fq * 8;
;     const bf16x8 bq0 = as_bf16x8(*(const u32x4*)qp), bq1 = as_bf16x8(*(const u32x4*)(qp + 32));
;     float m_run = -1e30f, l_run = 0.f;
;     f32x4 O[4];
; #pragma unroll
;     for (int db = 0; db < 4; ++db) O[db] = (f32x4){0.f, 0.f, 0.f, 0.f};
;     const bf16_t* vt = VT + (size_t)((b * 6 + h) * 64 + fr) * VTW;
;     const int rs = min(max(r - 4, 0), 120), kc0 = min(max(c0 - 8, 0), 32);
;     const int qcol = c0 + fr, cs = min(max(qcol - 8, 0), 48);
.LBB0_560:
	s_andn2_b64 vcc, exec, s[18:19]
	s_cbranch_vccnz .LBB0_694
	s_lshl_b32 s2, s54, 4
	s_and_b32 s2, s2, 48
	v_and_b32_e32 v118, 15, v84
	v_or_b32_e32 v8, s2, v118
	v_lshrrev_b32_e32 v6, 4, v85
	v_sub_u32_e64 v7, s2, 8 clamp
	v_sub_u32_e64 v9, v8, 8 clamp
	v_min_u32_e32 v7, 32, v7
	v_min_u32_e32 v9, 48, v9
	v_lshlrev_b32_e32 v78, 2, v6
	v_lshlrev_b32_e32 v4, 3, v6
	v_add_u32_e32 v106, v7, v78
	v_add_u32_e32 v6, 16, v9
	v_or_b32_e32 v10, s61, v7
	v_cmp_ge_u32_e32 vcc, v106, v9
	v_cmp_lt_u32_e64 s[38:39], v106, v6
	v_or_b32_e32 v7, 1, v106
	v_add_u32_e32 v105, v10, v118
	s_and_b64 s[46:47], vcc, s[38:39]
	v_cmp_ge_u32_e32 vcc, v7, v9
	v_cmp_lt_u32_e64 s[38:39], v7, v6
	v_or_b32_e32 v10, 2, v106
	s_and_b64 s[48:49], vcc, s[38:39]
	v_cmp_ge_u32_e32 vcc, v10, v9
	v_cmp_lt_u32_e64 s[38:39], v10, v6
	v_or_b32_e32 v11, 3, v106
	s_and_b64 s[50:51], vcc, s[38:39]
	v_cmp_ge_u32_e32 vcc, v11, v9
	v_cmp_lt_u32_e64 s[38:39], v11, v6
	v_add_u32_e32 v12, 16, v106
	s_and_b64 s[52:53], vcc, s[38:39]
	v_cmp_ge_u32_e32 vcc, v12, v9
	v_cmp_lt_u32_e64 s[38:39], v106, v9
	v_add_u32_e32 v13, 17, v106
	s_bfe_u32 s0, s54, 0x10002
	s_and_b64 s[54:55], vcc, s[38:39]
	v_cmp_ge_u32_e32 vcc, v13, v9
	v_cmp_lt_u32_e64 s[38:39], v13, v6
	v_add_u32_e32 v14, 18, v106
	s_and_b64 s[56:57], vcc, s[38:39]
	v_cmp_ge_u32_e32 vcc, v14, v9
	v_cmp_lt_u32_e64 s[38:39], v14, v6
	v_add_u32_e32 v15, 19, v106
	s_and_b64 s[58:59], vcc, s[38:39]
	v_cmp_ge_u32_e32 vcc, v15, v9
	v_and_b32_e32 v9, 64, v228
	v_cmp_lt_u32_e64 s[38:39], v15, v6
	v_xor_b32_e32 v6, 16, v228
	v_add_u32_e32 v9, 64, v9
	s_and_b64 s[38:39], vcc, s[38:39]
	v_cmp_lt_i32_e32 vcc, v6, v9
	v_readlane_b32 s4, v251, 18
	v_lshlrev_b32_e32 v0, 4, v84
	v_cndmask_b32_e32 v6, v228, v6, vcc
	v_lshlrev_b32_e32 v119, 2, v6
	v_xor_b32_e32 v6, 32, v228
	v_cmp_lt_i32_e32 vcc, v6, v9
	s_or_b32 s3, s61, s2
	v_and_b32_e32 v0, 0x70, v0
	v_cndmask_b32_e32 v6, v228, v6, vcc
	v_lshlrev_b32_e32 v120, 2, v6
	v_and_b32_e32 v6, 48, v84
	v_add_u32_e32 v16, 16, v6
	v_sub_u32_e32 v6, v106, v8
	v_max_i32_e32 v6, -15, v6
	v_add_u32_e32 v6, 15, v6
	v_min_u32_e32 v108, 30, v6
	v_sub_u32_e32 v6, v7, v8
	v_max_i32_e32 v6, -15, v6
	v_add_u32_e32 v6, 15, v6
	v_min_u32_e32 v109, 30, v6
	v_sub_u32_e32 v6, v10, v8
	v_max_i32_e32 v6, -15, v6
	v_add_u32_e32 v6, 15, v6
	v_min_u32_e32 v110, 30, v6
	v_sub_u32_e32 v6, v11, v8
	v_max_i32_e32 v6, -15, v6
	v_add_u32_e32 v6, 15, v6
	v_min_u32_e32 v111, 30, v6
	v_sub_u32_e32 v6, v12, v8
	v_max_i32_e32 v6, -15, v6
	v_add_u32_e32 v6, 15, v6
	v_min_u32_e32 v112, 30, v6
	v_sub_u32_e32 v6, v13, v8
	v_max_i32_e32 v6, -15, v6
	v_add_u32_e32 v6, 15, v6
	v_min_u32_e32 v113, 30, v6
	v_sub_u32_e32 v6, v14, v8
	v_max_i32_e32 v6, -15, v6
	v_add_u32_e32 v6, 15, v6
	v_min_u32_e32 v114, 30, v6
	v_sub_u32_e32 v6, v15, v8
	v_max_i32_e32 v6, -15, v6
	v_add_u32_e32 v6, 15, v6
	v_ashrrev_i32_e32 v10, 3, v84
	v_min_u32_e32 v115, 30, v6
	v_add_u32_e32 v8, s4, v10
	v_mov_b64_e32 v[6:7], s[40:41]
	v_or_b32_e32 v104, s3, v118
	v_mad_i64_i32 v[8:9], s[2:3], v8, s83, v[6:7]
	v_add_u32_e32 v11, 0x200, v84
	v_lshl_add_u64 v[8:9], v[8:9], 0, v[0:1]
	s_mov_b64 s[18:19], 0x1240
	v_ashrrev_i32_e32 v12, 3, v11
	v_lshl_add_u64 v[82:83], v[8:9], 0, s[18:19]
	v_add_u32_e32 v8, s4, v12
	v_mad_i64_i32 v[8:9], s[2:3], v8, s83, v[6:7]
	v_add_u32_e32 v13, 0x400, v84
	v_lshl_add_u64 v[8:9], v[8:9], 0, v[0:1]
	v_ashrrev_i32_e32 v14, 3, v13
	v_lshl_add_u64 v[86:87], v[8:9], 0, s[18:19]
	v_add_u32_e32 v8, s4, v14
	v_mad_i64_i32 v[8:9], s[2:3], v8, s83, v[6:7]
	v_lshl_add_u64 v[8:9], v[8:9], 0, v[0:1]
	s_movk_i32 s5, 0x90
	v_lshl_add_u64 v[88:89], v[8:9], 0, s[18:19]
	v_add_u32_e32 v9, 0x600, v84
	v_mul_lo_u32 v8, v14, s5
	v_ashrrev_i32_e32 v14, 3, v9
	v_add_u32_e32 v15, s4, v14
	v_lshlrev_b32_e32 v2, 3, v84
	v_mad_i64_i32 v[6:7], s[2:3], v15, s83, v[6:7]
	v_and_b32_e32 v2, 0xf8, v2
	s_movk_i32 s6, 0x210
	v_lshl_add_u64 v[6:7], v[6:7], 0, v[0:1]
	v_ashrrev_i32_e32 v116, 5, v84
	v_ashrrev_i32_e32 v117, 5, v11
	v_ashrrev_i32_e32 v121, 5, v13
	v_ashrrev_i32_e32 v122, 5, v9
	v_add_u32_e32 v3, 16, v0
	v_lshl_add_u32 v5, v2, 1, 16
	v_mul_u32_u24_e32 v17, 0x90, v118
	v_add_u32_e32 v18, 16, v4
	v_mul_u32_u24_e32 v19, 0x210, v118
	v_mad_u32_u24 v20, v118, s6, v231
	v_mad_u32_u24 v21, v118, s6, v232
	v_mul_lo_u32 v10, v10, s5
	v_mul_lo_u32 v12, v12, s5
	v_lshl_add_u64 v[90:91], v[6:7], 0, s[18:19]
	v_mul_lo_u32 v0, v14, s5
	v_mul_lo_u32 v6, v116, s6
	v_mul_lo_u32 v7, v117, s6
	v_mul_lo_u32 v11, v121, s6
	v_mul_lo_u32 v9, v122, s6
	v_add_u32_e32 v107, 16, v105
	s_mov_b32 s22, 0
	v_mov_b32_e32 v79, v1
	v_add_u32_e32 v123, v3, v10
	v_add_u32_e32 v124, v3, v12
	v_add_u32_e32 v125, v3, v8
	v_add_u32_e32 v126, v3, v0
	v_lshlrev_b32_e32 v0, 1, v2
	v_add_u32_e32 v127, v5, v6
	v_add_u32_e32 v128, v5, v7
	v_add_u32_e32 v129, v5, v11
	v_add_u32_e32 v130, v5, v9
	v_lshlrev_b32_e32 v80, 1, v4
	v_add_u32_e32 v131, v16, v17
	v_add_u32_e32 v132, v18, v19
	v_add_u32_e32 v133, v18, v20
	v_add_u32_e32 v134, v18, v21
	v_mul_u32_u24_e32 v254, 0x490, v118
	v_lshl_add_u32 v254, v106, 1, v254
	v_add_u32_e32 v243, 0x14810, v254
	v_add_u32_e32 v244, 0x19110, v254
	v_add_u32_e32 v245, 0x1da10, v254
	v_add_u32_e32 v246, 0x22310, v254
	v_mov_b32_e32 v254, v84
	v_mul_u32_u24_e32 v255, 0x71c8, v254
	v_lshrrev_b32_e32 v255, 21, v255
	v_mul_u32_u24_e32 v216, 72, v255
	v_sub_u32_e32 v254, v254, v216
	v_lshlrev_b32_e32 v254, 4, v254
	v_mul_u32_u24_e32 v216, 0x4200, v255
	v_add_u32_e32 v216, v216, v254
	v_mul_u32_u24_e32 v225, 0x490, v255
	v_add_u32_e32 v225, v225, v254
	v_add_u32_e32 v225, 0x14810, v225
	v_add_u32_e32 v254, 0x200, v84
	v_mul_u32_u24_e32 v255, 0x71c8, v254
	v_lshrrev_b32_e32 v255, 21, v255
; template <int MODE> ...
;     ...
;             mx = fmaxf(mx, fmaxf(fmaxf(acc[0], acc[1]), fmaxf(acc[2], acc[3])));
;         }
;         __builtin_amdgcn_sched_barrier(0);
;     }
;     mx = fmaxf(mx, __shfl_xor(mx, 16)); mx = fmaxf(mx, __shfl_xor(mx, 32));
; __device__ __forceinline__ void na_phase(ParamsK p, int l, unsigned char* smem, bool with_ctx) {
;     ...
;         for (int round = 0; round < NL / 256; ++round) {
;             const int w = lw + 256 * round, cq = w & 3, rr = (w >> 2) & 1, h = (w >> 3) % 6, r = (w / 48) * 2 + rr;
;             __syncthreads();
; #pragma unroll
;             for (int i = 0; i < 4; ++i) { const int idx = i * 512 + tid, key = idx >> 3, part = idx & 7;
;                 *(u32x4*)(Kc + key * 72 + part * 8) = *(const u32x4*)(U + (size_t)(TL + b * CTXL + key) * INP + NK0 + h * 64 + part * 8); }
; #pragma unroll
;             for (int i = 0; i < 4; ++i) { const int idx = i * 512 + tid, d = idx >> 5, part = idx & 31;
;                 *(u32x4*)(Vc + d * 264 + part * 8) = *(const u32x4*)(VT + (size_t)((b * 6 + h) * 64 + d) * VTW + SEQ + part * 8); }
;             __syncthreads();
;             na_tile<true>(U, VT, MIX, rpbL, Kc, Vc, true, b, r, cq * 16, b * SEQ + r * 64 + cq * 16, h, lane);
	v_mul_u32_u24_e32 v217, 72, v255
	v_sub_u32_e32 v254, v254, v217
	v_lshlrev_b32_e32 v254, 4, v254
	v_mul_u32_u24_e32 v217, 0x4200, v255
	v_add_u32_e32 v217, v217, v254
	v_mul_u32_u24_e32 v226, 0x490, v255
	v_add_u32_e32 v226, v226, v254
	v_add_u32_e32 v226, 0x14810, v226
	v_add_u32_e32 v254, 0x400, v84
	v_mul_u32_u24_e32 v255, 0x71c8, v254
	v_lshrrev_b32_e32 v255, 21, v255
	v_mul_u32_u24_e32 v218, 72, v255
	v_sub_u32_e32 v254, v254, v218
	v_lshlrev_b32_e32 v254, 4, v254
	v_mul_u32_u24_e32 v218, 0x4200, v255
	v_add_u32_e32 v218, v218, v254
	v_mul_u32_u24_e32 v227, 0x490, v255
	v_add_u32_e32 v227, v227, v254
	v_add_u32_e32 v227, 0x14810, v227
	v_add_u32_e32 v254, 0x600, v84
	v_mul_u32_u24_e32 v255, 0x71c8, v254
	v_lshrrev_b32_e32 v255, 21, v255
	v_mul_u32_u24_e32 v219, 72, v255
	v_sub_u32_e32 v254, v254, v219
	v_lshlrev_b32_e32 v254, 4, v254
	v_mul_u32_u24_e32 v219, 0x4200, v255
	v_add_u32_e32 v219, v219, v254
	v_mul_u32_u24_e32 v237, 0x490, v255
	v_add_u32_e32 v237, v237, v254
	v_add_u32_e32 v237, 0x14810, v237
	v_add_u32_e32 v254, 0x800, v84
	v_mul_u32_u24_e32 v255, 0x71c8, v254
	v_lshrrev_b32_e32 v255, 21, v255
	v_mul_u32_u24_e32 v220, 72, v255
	v_sub_u32_e32 v254, v254, v220
	v_lshlrev_b32_e32 v254, 4, v254
	v_mul_u32_u24_e32 v220, 0x4200, v255
	v_add_u32_e32 v220, v220, v254
	v_mul_u32_u24_e32 v238, 0x490, v255
	v_add_u32_e32 v238, v238, v254
	v_add_u32_e32 v238, 0x14810, v238
	v_add_u32_e32 v254, 0xa00, v84
	v_mul_u32_u24_e32 v255, 0x71c8, v254
	v_lshrrev_b32_e32 v255, 21, v255
	v_mul_u32_u24_e32 v221, 72, v255
	v_sub_u32_e32 v254, v254, v221
	v_lshlrev_b32_e32 v254, 4, v254
	v_mul_u32_u24_e32 v221, 0x4200, v255
	v_add_u32_e32 v221, v221, v254
	v_mul_u32_u24_e32 v239, 0x490, v255
	v_add_u32_e32 v239, v239, v254
	v_add_u32_e32 v239, 0x14810, v239
	v_add_u32_e32 v254, 0xc00, v84
	v_mul_u32_u24_e32 v255, 0x71c8, v254
	v_lshrrev_b32_e32 v255, 21, v255
	v_mul_u32_u24_e32 v222, 72, v255
	v_sub_u32_e32 v254, v254, v222
	v_lshlrev_b32_e32 v254, 4, v254
	v_mul_u32_u24_e32 v222, 0x4200, v255
	v_add_u32_e32 v222, v222, v254
	v_mul_u32_u24_e32 v240, 0x490, v255
	v_add_u32_e32 v240, v240, v254
	v_add_u32_e32 v240, 0x14810, v240
	v_add_u32_e32 v254, 0xe00, v84
	v_mul_u32_u24_e32 v255, 0x71c8, v254
	v_lshrrev_b32_e32 v255, 21, v255
	v_mul_u32_u24_e32 v223, 72, v255
	v_sub_u32_e32 v254, v254, v223
	v_lshlrev_b32_e32 v254, 4, v254
	v_mul_u32_u24_e32 v223, 0x4200, v255
	v_add_u32_e32 v223, v223, v254
	v_mul_u32_u24_e32 v241, 0x490, v255
	v_add_u32_e32 v241, v241, v254
	v_add_u32_e32 v241, 0x14810, v241
	v_add_u32_e32 v254, 0x1000, v84
	v_mul_u32_u24_e32 v255, 0x71c8, v254
	v_lshrrev_b32_e32 v255, 21, v255
	v_mul_u32_u24_e32 v224, 72, v255
	v_sub_u32_e32 v254, v254, v224
	v_lshlrev_b32_e32 v254, 4, v254
	v_mul_u32_u24_e32 v224, 0x4200, v255
	v_add_u32_e32 v224, v224, v254
	v_mul_u32_u24_e32 v242, 0x490, v255
	v_add_u32_e32 v242, v242, v254
	v_add_u32_e32 v242, 0x14810, v242
	s_branch .LBB0_563
.LBB0_562:
	s_or_b64 exec, exec, s[18:19]
	v_or_b32_e32 v10, s3, v118
	v_mul_i32_i24_e32 v10, 0x4200, v10
	v_ashrrev_i32_e32 v11, 31, v10
	v_lshl_add_u64 v[46:47], s[44:45], 0, v[10:11]
	v_max_f32_e32 v10, v41, v41
	v_max_f32_e32 v11, v42, v42
	v_max_f32_e32 v10, v11, v10
	v_max_f32_e32 v11, v43, v43
	v_max_f32_e32 v14, v44, v44
	v_max_f32_e32 v11, v14, v11
	v_max3_f32 v10, v39, v38, v10
	v_max3_f32 v11, v45, v40, v11
	v_max3_f32 v10, v10, s69, v11
	v_max_f32_e32 v11, v50, v50
	v_max_f32_e32 v14, v52, v52
	v_max_f32_e32 v11, v14, v11
	v_max_f32_e32 v14, v54, v54
	v_max_f32_e32 v15, v55, v55
	v_max_f32_e32 v14, v15, v14
	v_max3_f32 v11, v49, v48, v11
	v_max3_f32 v14, v53, v51, v14
	v_max3_f32 v10, v10, v11, v14
	v_max_f32_e32 v11, v58, v58
	v_max_f32_e32 v14, v61, v61
	v_max_f32_e32 v11, v14, v11
	v_max_f32_e32 v14, v69, v69
	v_max_f32_e32 v15, v71, v71
	v_max_f32_e32 v14, v15, v14
	v_max3_f32 v11, v57, v56, v11
	v_max3_f32 v14, v63, v62, v14
	v_max3_f32 v10, v10, v11, v14
	v_max_f32_e32 v11, v72, v72
	v_max_f32_e32 v14, v74, v74
	v_max_f32_e32 v11, v14, v11
	v_max_f32_e32 v14, v76, v76
	v_max_f32_e32 v15, v77, v77
	v_max_f32_e32 v14, v15, v14
	v_max3_f32 v11, v70, v68, v11
	v_max3_f32 v14, v75, v73, v14
	v_max3_f32 v10, v10, v11, v14
	v_max_f32_e32 v11, v95, v95
	v_max_f32_e32 v14, v97, v97
	v_max_f32_e32 v11, v14, v11
	v_max_f32_e32 v14, v98, v98
	v_max_f32_e32 v15, v100, v100
	v_max_f32_e32 v14, v15, v14
	v_max3_f32 v11, v93, v92, v11
	v_max3_f32 v14, v96, v94, v14
	v_max3_f32 v10, v10, v11, v14
	v_max_f32_e32 v11, v102, v102
	v_max_f32_e32 v14, v103, v103
	v_max_f32_e32 v11, v14, v11
	v_max_f32_e32 v14, v137, v137
	v_max_f32_e32 v15, v138, v138
	v_max_f32_e32 v14, v15, v14
	v_max3_f32 v11, v101, v99, v11
	v_max3_f32 v14, v136, v135, v14
	v_max3_f32 v10, v10, v11, v14
	v_max_f32_e32 v11, v36, v36
	v_max_f32_e32 v14, v37, v37
	v_max_f32_e32 v11, v14, v11
	v_max_f32_e32 v14, v143, v143
	v_max_f32_e32 v15, v144, v144
	v_max_f32_e32 v14, v15, v14
	v_max3_f32 v11, v140, v139, v11
	v_max3_f32 v14, v142, v141, v14
	v_max3_f32 v10, v10, v11, v14
	v_max_f32_e32 v11, v147, v147
	v_max_f32_e32 v14, v148, v148
	v_max_f32_e32 v11, v14, v11
	v_max_f32_e32 v14, v12, v12
	v_max_f32_e32 v15, v13, v13
	v_max_f32_e32 v14, v15, v14
	v_max3_f32 v11, v146, v145, v11
	v_max3_f32 v14, v60, v59, v14
	v_ashrrev_i32_e32 v85, 31, v84
	v_max3_f32 v10, v10, v11, v14
	ds_bpermute_b32 v11, v119, v10
	v_mov_b32_e32 v23, v1
	s_waitcnt lgkmcnt(0)
	v_max_f32_e32 v11, v11, v11
	v_max_f32_e32 v10, v10, v11
	ds_bpermute_b32 v11, v120, v10
	s_waitcnt lgkmcnt(0)
; __device__ __forceinline__ unsigned pk2(float lo, float hi) { return pg8::cvt_pk_bf16(lo, hi); }
; #define EX2(x) __builtin_amdgcn_exp2f(x)
; template <int MODE> ...
;     ...
;     const float m_new = fmaxf(m_run, mx), alpha = EX2(m_run - m_new);
;     float lsum = 0.f; unsigned pkd[16][2];
; #pragma unroll
;     for (int kb = 0; kb < 16; ++kb) { const float p0 = EX2(s[kb][0] - m_new), p1 = EX2(s[kb][1] - m_new), p2 = EX2(s[kb][2] - m_new), p3 = EX2(s[kb][3] - m_new);
;         lsum += (p0 + p1) + (p2 + p3); pkd[kb][0] = pk2(p0, p1); pkd[kb][1] = pk2(p2, p3); }
;     lsum += __shfl_xor(lsum, 16); lsum += __shfl_xor(lsum, 32);
;     l_run = l_run * alpha + lsum; m_run = m_new;
	v_max3_f32 v81, v10, v11, s69
	v_sub_f32_e32 v11, v38, v81
	v_sub_f32_e32 v10, v39, v81
	v_exp_f32_e32 v14, v11
	v_sub_f32_e32 v11, v42, v81
	v_sub_f32_e32 v15, v41, v81
	v_exp_f32_e32 v10, v10
	v_exp_f32_e32 v11, v11
	v_exp_f32_e32 v15, v15
	v_sub_f32_e32 v22, v50, v81
	v_exp_f32_e32 v22, v22
	v_sub_f32_e32 v12, v12, v81
	v_pk_add_f32 v[16:17], v[10:11], v[14:15]
	v_cvt_pk_bf16_f32 v15, v11, v15
	v_sub_f32_e32 v11, v40, v81
	v_pk_add_f32 v[20:21], v[16:17], v[16:17] op_sel_hi:[0,1]
	v_exp_f32_e32 v16, v11
	v_sub_f32_e32 v11, v44, v81
	v_cvt_pk_bf16_f32 v14, v10, v14
	v_sub_f32_e32 v10, v45, v81
	v_exp_f32_e32 v17, v11
	v_sub_f32_e32 v11, v43, v81
	v_exp_f32_e32 v10, v10
	v_exp_f32_e32 v18, v11
	v_sub_f32_e32 v20, v52, v81
	v_exp_f32_e32 v20, v20
	v_add_f32_e32 v11, v10, v16
	v_add_f32_e32 v19, v17, v18
	v_cvt_pk_bf16_f32 v16, v10, v16
	v_cvt_pk_bf16_f32 v17, v17, v18
	v_sub_f32_e32 v10, v49, v81
	v_sub_f32_e32 v18, v48, v81
	v_exp_f32_e32 v10, v10
	v_exp_f32_e32 v18, v18
	v_pk_add_f32 v[26:27], v[20:21], v[22:23]
	v_sub_f32_e32 v21, v54, v81
	v_exp_f32_e32 v21, v21
	v_pk_add_f32 v[24:25], v[10:11], v[18:19]
	v_sub_f32_e32 v11, v51, v81
	v_cvt_pk_bf16_f32 v18, v10, v18
	v_cvt_pk_bf16_f32 v19, v20, v22
	v_sub_f32_e32 v10, v53, v81
	v_exp_f32_e32 v20, v11
	v_sub_f32_e32 v11, v55, v81
	v_exp_f32_e32 v10, v10
	v_exp_f32_e32 v11, v11
	v_pk_add_f32 v[24:25], v[24:25], v[26:27]
	v_sub_f32_e32 v64, 0xf149f2ca, v81
	v_pk_add_f32 v[26:27], v[24:25], v[24:25] op_sel_hi:[0,1]
	v_pk_add_f32 v[22:23], v[10:11], v[20:21]
	v_cvt_pk_bf16_f32 v21, v11, v21
	v_sub_f32_e32 v11, v56, v81
	v_pk_add_f32 v[28:29], v[22:23], v[22:23] op_sel_hi:[0,1]
	v_exp_f32_e32 v22, v11
	v_sub_f32_e32 v11, v61, v81
	v_cvt_pk_bf16_f32 v20, v10, v20
	v_sub_f32_e32 v10, v57, v81
	v_exp_f32_e32 v23, v11
	v_sub_f32_e32 v11, v58, v81
	v_exp_f32_e32 v10, v10
	v_exp_f32_e32 v24, v11
	v_sub_f32_e32 v26, v71, v81
	v_exp_f32_e32 v28, v26
	v_add_f32_e32 v11, v10, v22
	v_add_f32_e32 v25, v23, v24
	v_cvt_pk_bf16_f32 v22, v10, v22
	v_cvt_pk_bf16_f32 v23, v23, v24
	v_sub_f32_e32 v10, v63, v81
	v_sub_f32_e32 v24, v62, v81
	v_exp_f32_e32 v10, v10
	v_exp_f32_e32 v24, v24
	v_sub_f32_e32 v26, v69, v81
	v_exp_f32_e32 v26, v26
	v_pk_add_f32 v[30:31], v[10:11], v[24:25]
	v_sub_f32_e32 v11, v68, v81
	v_pk_add_f32 v[32:33], v[28:29], v[26:27]
	v_cvt_pk_bf16_f32 v24, v10, v24
	v_cvt_pk_bf16_f32 v25, v28, v26
	v_sub_f32_e32 v10, v70, v81
	v_exp_f32_e32 v26, v11
	v_sub_f32_e32 v11, v74, v81
	v_sub_f32_e32 v27, v72, v81
	v_exp_f32_e32 v10, v10
	v_exp_f32_e32 v11, v11
	v_exp_f32_e32 v27, v27
	v_pk_add_f32 v[30:31], v[30:31], v[32:33]
	v_pk_add_f32 v[28:29], v[10:11], v[26:27]
	v_cvt_pk_bf16_f32 v27, v11, v27
	v_sub_f32_e32 v11, v73, v81
	v_pk_add_f32 v[34:35], v[28:29], v[28:29] op_sel_hi:[0,1]
	v_exp_f32_e32 v28, v11
	v_sub_f32_e32 v11, v77, v81
	v_cvt_pk_bf16_f32 v26, v10, v26
	v_sub_f32_e32 v10, v75, v81
	v_exp_f32_e32 v29, v11
	v_sub_f32_e32 v11, v76, v81
	v_pk_add_f32 v[32:33], v[30:31], v[30:31] op_sel_hi:[0,1]
	v_exp_f32_e32 v10, v10
	v_exp_f32_e32 v30, v11
	v_sub_f32_e32 v32, v97, v81
	v_exp_f32_e32 v34, v32
	v_add_f32_e32 v11, v10, v28
	v_add_f32_e32 v31, v29, v30
	v_cvt_pk_bf16_f32 v28, v10, v28
	v_cvt_pk_bf16_f32 v29, v29, v30
	v_sub_f32_e32 v10, v93, v81
	v_sub_f32_e32 v30, v92, v81
	v_exp_f32_e32 v10, v10
	v_exp_f32_e32 v30, v30
	v_sub_f32_e32 v32, v95, v81
	v_exp_f32_e32 v32, v32
	v_pk_add_f32 v[38:39], v[10:11], v[30:31]
	v_sub_f32_e32 v11, v94, v81
	v_pk_add_f32 v[40:41], v[34:35], v[32:33]
	v_cvt_pk_bf16_f32 v30, v10, v30
	v_cvt_pk_bf16_f32 v31, v34, v32
	v_sub_f32_e32 v10, v96, v81
	v_exp_f32_e32 v32, v11
	v_sub_f32_e32 v11, v100, v81
	v_sub_f32_e32 v33, v98, v81
	v_exp_f32_e32 v10, v10
	v_exp_f32_e32 v11, v11
	v_exp_f32_e32 v33, v33
	v_pk_add_f32 v[38:39], v[38:39], v[40:41]
	v_pk_add_f32 v[34:35], v[10:11], v[32:33]
	s_nop 0
	v_pk_add_f32 v[34:35], v[34:35], v[34:35] op_sel_hi:[0,1]
	v_cvt_pk_bf16_f32 v33, v11, v33
	v_sub_f32_e32 v11, v99, v81
	v_pk_add_f32 v[38:39], v[38:39], v[38:39] op_sel_hi:[0,1]
	v_cvt_pk_bf16_f32 v32, v10, v32
	v_sub_f32_e32 v10, v101, v81
	v_exp_f32_e32 v34, v11
	v_sub_f32_e32 v11, v103, v81
	v_exp_f32_e32 v10, v10
	v_exp_f32_e32 v38, v11
	v_sub_f32_e32 v11, v102, v81
	v_exp_f32_e32 v40, v11
	v_add_f32_e32 v11, v10, v34
	v_cvt_pk_bf16_f32 v42, v10, v34
	v_sub_f32_e32 v34, v135, v81
	v_add_f32_e32 v41, v38, v40
	v_cvt_pk_bf16_f32 v43, v38, v40
	v_sub_f32_e32 v10, v136, v81
	v_exp_f32_e32 v40, v34
	v_sub_f32_e32 v34, v138, v81
	v_sub_f32_e32 v38, v137, v81
	v_exp_f32_e32 v10, v10
	v_exp_f32_e32 v34, v34
	v_exp_f32_e32 v38, v38
	v_pk_add_f32 v[44:45], v[10:11], v[40:41]
	v_sub_f32_e32 v11, v139, v81
	v_pk_add_f32 v[48:49], v[34:35], v[38:39]
	v_sub_f32_e32 v35, v36, v81
	v_pk_add_f32 v[44:45], v[44:45], v[48:49]
	v_exp_f32_e32 v35, v35
	v_pk_add_f32 v[48:49], v[44:45], v[44:45] op_sel_hi:[0,1]
	v_cvt_pk_bf16_f32 v44, v10, v40
	v_cvt_pk_bf16_f32 v45, v34, v38
	v_sub_f32_e32 v10, v140, v81
	v_exp_f32_e32 v34, v11
	v_sub_f32_e32 v11, v37, v81
	v_exp_f32_e32 v10, v10
	v_exp_f32_e32 v11, v11
	v_sub_f32_e32 v48, v147, v81
	v_exp_f32_e32 v48, v48
	v_pk_add_f32 v[36:37], v[10:11], v[34:35]
	v_cvt_pk_bf16_f32 v35, v11, v35
	v_sub_f32_e32 v11, v141, v81
	v_pk_add_f32 v[40:41], v[36:37], v[36:37] op_sel_hi:[0,1]
	v_exp_f32_e32 v36, v11
	v_sub_f32_e32 v11, v144, v81
	v_cvt_pk_bf16_f32 v34, v10, v34
	v_sub_f32_e32 v10, v142, v81
	v_exp_f32_e32 v37, v11
	v_sub_f32_e32 v11, v143, v81
	v_exp_f32_e32 v10, v10
	v_exp_f32_e32 v38, v11
	v_sub_f32_e32 v40, v148, v81
	v_exp_f32_e32 v40, v40
	v_add_f32_e32 v11, v10, v36
	v_add_f32_e32 v39, v37, v38
	v_cvt_pk_bf16_f32 v36, v10, v36
; template <int MODE> ...
;     ...
;     for (int kg = 0; kg < 4; ++kg) {
;         bf16x8 ka0[4], ka1[4];
; #pragma unroll
;         for (int i = 0; i < 4; ++i) { const int kb = kg * 4 + i;
;             if (MODE == 2) { const bf16_t* kp = Kc + (kb * 16 + fr) * 72 + fq * 8; ka0[i] = as_bf16x8(*(const u32x4*)kp); ka1[i] = as_bf16x8(*(const u32x4*)(kp + 32)); }
;             else { const int krow = MODE == 0 ? (b * SEQ + (rs + (kb >> 1)) * 64 + kc0 + (kb & 1) * 16 + fr) : (TL + b * CTXL + kb * 16 + fr);
;                 const bf16_t* kp = U + (size_t)krow * INP + NK0 + h * 64 + fq * 8; ka0[i] = as_bf16x8(*(const u32x4*)kp); ka1[i] = as_bf16x8(*(const u32x4*)(kp + 32)); } }
;         __builtin_amdgcn_sched_barrier(0);
; #pragma unroll
;         for (int i = 0; i < 4; ++i) { const int kb = kg * 4 + i;
;             f32x4 acc = (f32x4){0.f, 0.f, 0.f, 0.f};
;             acc = __builtin_amdgcn_mfma_f32_16x16x32_bf16(ka0[i], bq0, acc, 0, 0, 0);
;             acc = __builtin_amdgcn_mfma_f32_16x16x32_bf16(ka1[i], bq1, acc, 0, 0, 0);
;     ...
; #pragma unroll
;     for (int pg = 0; pg < 4; ++pg) {
;         u32x2 vlo[2][4], vhi[2][4];
; #pragma unroll
;         for (int i = 0; i < 2; ++i) { const int pr = pg * 2 + i;
;             const int posA = MODE == 0 ? ((rs + pr) * 64 + kc0 + fq * 4) : (SEQ + pr * 32 + fq * 4);
; #pragma unroll
;             for (int db = 0; db < 4; ++db) {
;                 if (MODE == 2) { const bf16_t* vp = Vc + (db * 16 + fr) * 264 + pr * 32 + fq * 4; vlo[i][db] = *(const u32x2*)vp; vhi[i][db] = *(const u32x2*)(vp + 16); }
;                 else { const bf16_t* vp = vt + (size_t)(db * 16) * VTW + posA; vlo[i][db] = *(const u32x2*)vp; vhi[i][db] = *(const u32x2*)(vp + 16); } } }
;         __builtin_amdgcn_sched_barrier(0);
; #pragma unroll
;         for (int i = 0; i < 2; ++i) { const int pr = pg * 2 + i;
;             u32x4 bw; bw.x = pkd[2 * pr][0]; bw.y = pkd[2 * pr][1]; bw.z = pkd[2 * pr + 1][0]; bw.w = pkd[2 * pr + 1][1];
;             const bf16x8 bp = as_bf16x8(bw);
; #pragma unroll
;             for (int db = 0; db < 4; ++db) { u32x4 aw; aw.x = vlo[i][db].x; aw.y = vlo[i][db].y; aw.z = vhi[i][db].x; aw.w = vhi[i][db].y;
;                 O[db] = __builtin_amdgcn_mfma_f32_16x16x32_bf16(as_bf16x8(aw), bp, O[db], 0, 0, 0); } }
;         __builtin_amdgcn_sched_barrier(0);
;     }
	v_cvt_pk_bf16_f32 v37, v37, v38
	v_sub_f32_e32 v10, v146, v81
	v_sub_f32_e32 v38, v145, v81
	v_exp_f32_e32 v10, v10
	v_exp_f32_e32 v38, v38
	v_pk_add_f32 v[52:53], v[40:41], v[48:49]
	v_mov_b32_e32 v49, v1
	v_exp_f32_e32 v41, v12
	v_pk_add_f32 v[50:51], v[10:11], v[38:39]
	v_cvt_pk_bf16_f32 v39, v40, v48
	v_add_u32_e32 v48, s2, v106
	v_lshl_add_u64 v[96:97], v[48:49], 1, v[46:47]
	v_sub_f32_e32 v11, v59, v81
	v_add_co_u32_e32 v98, vcc, s75, v96
	v_cvt_pk_bf16_f32 v38, v10, v38
	v_sub_f32_e32 v10, v60, v81
	v_exp_f32_e32 v40, v11
	v_sub_f32_e32 v11, v13, v81
	v_addc_co_u32_e32 v99, vcc, 0, v97, vcc
	v_exp_f32_e32 v10, v10
	v_exp_f32_e32 v11, v11
	v_add_co_u32_e32 v100, vcc, s76, v96
	v_pk_add_f32 v[92:93], v[50:51], v[52:53]
	s_nop 0
	v_addc_co_u32_e32 v101, vcc, 0, v97, vcc
	v_add_co_u32_e32 v102, vcc, s77, v96
	v_pk_add_f32 v[94:95], v[10:11], v[40:41]
	s_nop 0
	v_addc_co_u32_e32 v103, vcc, 0, v97, vcc
	v_cvt_pk_bf16_f32 v40, v10, v40
	v_exp_f32_e32 v10, v64
	ds_read2_b64 v[46:49], v247 offset0:0 offset1:4
	ds_read2_b64 v[50:53], v248 offset0:0 offset1:4
	ds_read2_b64 v[54:57], v249 offset0:0 offset1:4
	ds_read2_b64 v[58:61], v253 offset0:0 offset1:4
	ds_read2_b64 v[62:65], v247 offset0:16 offset1:20
	ds_read2_b64 v[66:69], v248 offset0:16 offset1:20
	ds_read2_b64 v[70:73], v249 offset0:16 offset1:20
	ds_read2_b64 v[74:77], v253 offset0:16 offset1:20
	v_mul_f32_e32 v10, 0, v10
	v_cvt_pk_bf16_f32 v41, v11, v41
	v_mov_b32_e32 v11, v10
	v_mov_b32_e32 v12, v10
	v_mov_b32_e32 v13, v10
	s_waitcnt lgkmcnt(7)
	s_nop 0
	v_mfma_f32_16x16x32_bf16 v[46:49], v[46:49], v[14:17], v[10:13]
	s_waitcnt lgkmcnt(6)
	v_mfma_f32_16x16x32_bf16 v[50:53], v[50:53], v[14:17], v[10:13]
	s_waitcnt lgkmcnt(5)
	v_mfma_f32_16x16x32_bf16 v[54:57], v[54:57], v[14:17], v[10:13]
	s_waitcnt lgkmcnt(4)
	v_mfma_f32_16x16x32_bf16 v[12:15], v[58:61], v[14:17], v[10:13]
	s_waitcnt lgkmcnt(3)
	v_mfma_f32_16x16x32_bf16 v[46:49], v[62:65], v[18:21], v[46:49]
	s_waitcnt lgkmcnt(2)
	v_mfma_f32_16x16x32_bf16 v[50:53], v[66:69], v[18:21], v[50:53]
	s_waitcnt lgkmcnt(1)
	v_mfma_f32_16x16x32_bf16 v[54:57], v[70:73], v[18:21], v[54:57]
	s_waitcnt lgkmcnt(0)
	v_mfma_f32_16x16x32_bf16 v[12:15], v[74:77], v[18:21], v[12:15]
	ds_read2_b64 v[16:19], v247 offset0:32 offset1:36
	ds_read2_b64 v[58:61], v247 offset0:48 offset1:52
	ds_read2_b64 v[62:65], v248 offset0:32 offset1:36
	ds_read2_b64 v[66:69], v248 offset0:48 offset1:52
	ds_read2_b64 v[70:73], v249 offset0:32 offset1:36
	ds_read2_b64 v[74:77], v249 offset0:48 offset1:52
	ds_read2_b64 v[136:139], v253 offset0:32 offset1:36
	ds_read2_b64 v[140:143], v253 offset0:48 offset1:52
	s_waitcnt lgkmcnt(7)
	v_mfma_f32_16x16x32_bf16 v[16:19], v[16:19], v[22:25], v[46:49]
	s_waitcnt lgkmcnt(5)
	v_mfma_f32_16x16x32_bf16 v[46:49], v[62:65], v[22:25], v[50:53]
	s_waitcnt lgkmcnt(3)
	v_mfma_f32_16x16x32_bf16 v[50:53], v[70:73], v[22:25], v[54:57]
	s_waitcnt lgkmcnt(1)
	v_mfma_f32_16x16x32_bf16 v[12:15], v[136:139], v[22:25], v[12:15]
	v_mfma_f32_16x16x32_bf16 v[16:19], v[58:61], v[26:29], v[16:19]
	v_mfma_f32_16x16x32_bf16 v[20:23], v[66:69], v[26:29], v[46:49]
	v_mfma_f32_16x16x32_bf16 v[46:49], v[74:77], v[26:29], v[50:53]
	s_waitcnt lgkmcnt(0)
	v_mfma_f32_16x16x32_bf16 v[12:15], v[140:143], v[26:29], v[12:15]
	ds_read2_b64 v[24:27], v247 offset0:64 offset1:68
	ds_read2_b64 v[50:53], v247 offset0:80 offset1:84
	ds_read2_b64 v[54:57], v248 offset0:64 offset1:68
	ds_read2_b64 v[58:61], v248 offset0:80 offset1:84
	ds_read2_b64 v[62:65], v249 offset0:64 offset1:68
	ds_read2_b64 v[66:69], v249 offset0:80 offset1:84
	ds_read2_b64 v[70:73], v253 offset0:64 offset1:68
	ds_read2_b64 v[74:77], v253 offset0:80 offset1:84
	s_waitcnt lgkmcnt(7)
	v_mfma_f32_16x16x32_bf16 v[16:19], v[24:27], v[30:33], v[16:19]
	s_waitcnt lgkmcnt(5)
	v_mfma_f32_16x16x32_bf16 v[20:23], v[54:57], v[30:33], v[20:23]
	s_waitcnt lgkmcnt(3)
	v_mfma_f32_16x16x32_bf16 v[24:27], v[62:65], v[30:33], v[46:49]
	s_waitcnt lgkmcnt(1)
	v_mfma_f32_16x16x32_bf16 v[12:15], v[70:73], v[30:33], v[12:15]
	v_mfma_f32_16x16x32_bf16 v[16:19], v[50:53], v[42:45], v[16:19]
	v_mfma_f32_16x16x32_bf16 v[20:23], v[58:61], v[42:45], v[20:23]
	v_mfma_f32_16x16x32_bf16 v[24:27], v[66:69], v[42:45], v[24:27]
	s_waitcnt lgkmcnt(0)
	v_mfma_f32_16x16x32_bf16 v[12:15], v[74:77], v[42:45], v[12:15]
	ds_read2_b64 v[28:31], v247 offset0:96 offset1:100
	ds_read2_b64 v[42:45], v247 offset0:112 offset1:116
	ds_read2_b64 v[46:49], v248 offset0:96 offset1:100
	ds_read2_b64 v[50:53], v248 offset0:112 offset1:116
	ds_read2_b64 v[54:57], v249 offset0:96 offset1:100
	ds_read2_b64 v[58:61], v249 offset0:112 offset1:116
	ds_read2_b64 v[62:65], v253 offset0:96 offset1:100
	ds_read2_b64 v[66:69], v253 offset0:112 offset1:116
	s_waitcnt lgkmcnt(7)
	v_mfma_f32_16x16x32_bf16 v[16:19], v[28:31], v[34:37], v[16:19]
	s_waitcnt lgkmcnt(5)
	v_mfma_f32_16x16x32_bf16 v[20:23], v[46:49], v[34:37], v[20:23]
	s_waitcnt lgkmcnt(3)
	v_mfma_f32_16x16x32_bf16 v[28:31], v[54:57], v[34:37], v[24:27]
	s_waitcnt lgkmcnt(1)
	v_mfma_f32_16x16x32_bf16 v[32:35], v[62:65], v[34:37], v[12:15]
	v_mfma_f32_16x16x32_bf16 v[24:27], v[42:45], v[38:41], v[16:19]
	v_mfma_f32_16x16x32_bf16 v[20:23], v[50:53], v[38:41], v[20:23]
	v_mfma_f32_16x16x32_bf16 v[12:15], v[58:61], v[38:41], v[28:31]
	s_waitcnt lgkmcnt(0)
	v_mfma_f32_16x16x32_bf16 v[16:19], v[66:69], v[38:41], v[32:35]
	s_nop 0
	ds_read_b128 v[28:31], v131 offset:12288
	s_nop 0
	ds_read_b128 v[32:35], v131 offset:12352
	ds_read_b128 v[36:39], v131 offset:14592
	ds_read_b128 v[40:43], v131 offset:14656
	ds_read_b128 v[44:47], v131 offset:16896
	ds_read_b128 v[48:51], v131 offset:16960
	ds_read_b128 v[52:55], v131 offset:19200
	ds_read_b128 v[56:59], v131 offset:19264
	s_waitcnt lgkmcnt(7)
; template <int MODE> ...
;     ...
;     for (int kg = 0; kg < 4; ++kg) {
;         bf16x8 ka0[4], ka1[4];
; #pragma unroll
;         for (int i = 0; i < 4; ++i) { const int kb = kg * 4 + i;
;             if (MODE == 2) { const bf16_t* kp = Kc + (kb * 16 + fr) * 72 + fq * 8; ka0[i] = as_bf16x8(*(const u32x4*)kp); ka1[i] = as_bf16x8(*(const u32x4*)(kp + 32)); }
;             else { const int krow = MODE == 0 ? (b * SEQ + (rs + (kb >> 1)) * 64 + kc0 + (kb & 1) * 16 + fr) : (TL + b * CTXL + kb * 16 + fr);
;                 const bf16_t* kp = U + (size_t)krow * INP + NK0 + h * 64 + fq * 8; ka0[i] = as_bf16x8(*(const u32x4*)kp); ka1[i] = as_bf16x8(*(const u32x4*)(kp + 32)); } }
;         __builtin_amdgcn_sched_barrier(0);
; #pragma unroll
;         for (int i = 0; i < 4; ++i) { const int kb = kg * 4 + i;
;             f32x4 acc = (f32x4){0.f, 0.f, 0.f, 0.f};
;             acc = __builtin_amdgcn_mfma_f32_16x16x32_bf16(ka0[i], bq0, acc, 0, 0, 0);
;             acc = __builtin_amdgcn_mfma_f32_16x16x32_bf16(ka1[i], bq1, acc, 0, 0, 0);
;             acc = acc * (0.125f * LOG2E);
;             if (MODE == 0) {
;                 const int dr = rs + (kb >> 1) - r + 7;
; #pragma unroll
;                 for (int j = 0; j < 4; ++j) { const int kcol = kc0 + (kb & 1) * 16 + fq * 4 + j; const bool valid = (kcol >= cs) && (kcol < cs + 16);
;                     const int dc = min(max(kcol - qcol + 15, 0), 30);
;                     acc[j] = valid ? acc[j] + rpbL[(h * 15 + dr) * 31 + dc] : -1e30f; }
;             }
;             s[kb] = acc;
;             mx = fmaxf(mx, fmaxf(fmaxf(acc[0], acc[1]), fmaxf(acc[2], acc[3])));
;         }
;         __builtin_amdgcn_sched_barrier(0);
;     }
	v_mfma_f32_16x16x32_bf16 v[28:31], v[28:31], v[6:9], 0
	s_waitcnt lgkmcnt(6)
	v_mfma_f32_16x16x32_bf16 v[28:31], v[32:35], v[2:5], v[28:31]
	s_waitcnt lgkmcnt(5)
	v_mfma_f32_16x16x32_bf16 v[32:35], v[36:39], v[6:9], 0
	s_nop 5
	v_mul_f32_e64 v76, v30, s36
	v_mul_f32_e64 v77, v31, s36
	s_waitcnt lgkmcnt(4)
	v_mfma_f32_16x16x32_bf16 v[30:33], v[40:43], v[2:5], v[32:35]
	v_mul_f32_e64 v140, v28, s36
	v_mul_f32_e64 v141, v29, s36
	v_max_f32_e32 v11, v76, v77
	v_max3_f32 v11, v140, v141, v11
	s_waitcnt lgkmcnt(3)
	v_mfma_f32_16x16x32_bf16 v[34:37], v[44:47], v[6:9], 0
	s_nop 1
	v_mul_f32_e64 v144, v30, s36
	v_mul_f32_e64 v145, v31, s36
	s_waitcnt lgkmcnt(2)
	v_mfma_f32_16x16x32_bf16 v[28:31], v[48:51], v[2:5], v[34:37]
	v_mul_f32_e64 v142, v32, s36
	v_mul_f32_e64 v143, v33, s36
	v_max_f32_e32 v32, v142, v143
	v_max3_f32 v32, v144, v145, v32
	v_max3_f32 v11, v11, s69, v32
	s_nop 2
	v_pk_mul_f32 v[146:147], v[30:31], s[36:37] op_sel_hi:[1,0]
	s_waitcnt lgkmcnt(1)
	v_mfma_f32_16x16x32_bf16 v[30:33], v[52:55], v[6:9], 0
	v_mul_f32_e64 v148, v28, s36
	v_mul_f32_e64 v149, v29, s36
	v_max_f32_e32 v28, v146, v147
	v_max3_f32 v34, v148, v149, v28
	s_waitcnt lgkmcnt(0)
	v_mfma_f32_16x16x32_bf16 v[28:31], v[56:59], v[2:5], v[30:33]
	s_nop 7
	v_pk_mul_f32 v[150:151], v[30:31], s[36:37] op_sel_hi:[1,0]
	v_pk_mul_f32 v[152:153], v[28:29], s[36:37] op_sel_hi:[1,0]
	v_max_f32_e32 v28, v150, v151
	v_max3_f32 v28, v152, v153, v28
	v_max3_f32 v11, v11, v34, v28
	ds_read_b128 v[28:31], v131 offset:21504
	ds_read_b128 v[32:35], v131 offset:21568
	ds_read_b128 v[36:39], v131 offset:23808
	ds_read_b128 v[40:43], v131 offset:23872
	ds_read_b128 v[44:47], v131 offset:26112
	ds_read_b128 v[48:51], v131 offset:26176
	ds_read_b128 v[52:55], v131 offset:28416
	ds_read_b128 v[56:59], v131 offset:28480
	s_waitcnt lgkmcnt(7)
	v_mfma_f32_16x16x32_bf16 v[28:31], v[28:31], v[6:9], 0
	s_waitcnt lgkmcnt(6)
	v_mfma_f32_16x16x32_bf16 v[28:31], v[32:35], v[2:5], v[28:31]
	s_waitcnt lgkmcnt(5)
	v_mfma_f32_16x16x32_bf16 v[32:35], v[36:39], v[6:9], 0
	s_nop 5
	v_mul_f32_e64 v154, v30, s36
	v_mul_f32_e64 v155, v31, s36
	s_waitcnt lgkmcnt(4)
	v_mfma_f32_16x16x32_bf16 v[30:33], v[40:43], v[2:5], v[32:35]
	v_mul_f32_e64 v156, v28, s36
	v_mul_f32_e64 v157, v29, s36
	v_max_f32_e32 v28, v154, v155
	v_max3_f32 v38, v156, v157, v28
	s_waitcnt lgkmcnt(3)
	v_mfma_f32_16x16x32_bf16 v[34:37], v[44:47], v[6:9], 0
	s_nop 1
	v_mul_f32_e64 v160, v30, s36
	v_mul_f32_e64 v161, v31, s36
	s_waitcnt lgkmcnt(2)
	v_mfma_f32_16x16x32_bf16 v[28:31], v[48:51], v[2:5], v[34:37]
	v_mul_f32_e64 v158, v32, s36
	v_mul_f32_e64 v159, v33, s36
	v_max_f32_e32 v32, v158, v159
	v_max3_f32 v32, v160, v161, v32
	v_max3_f32 v11, v11, v38, v32
	s_nop 2
	v_pk_mul_f32 v[42:43], v[30:31], s[36:37] op_sel_hi:[1,0]
	s_waitcnt lgkmcnt(1)
	v_mfma_f32_16x16x32_bf16 v[30:33], v[52:55], v[6:9], 0
	v_mul_f32_e64 v176, v28, s36
	v_mul_f32_e64 v177, v29, s36
	v_max_f32_e32 v28, v42, v43
	v_max3_f32 v34, v176, v177, v28
	s_waitcnt lgkmcnt(0)
	v_mfma_f32_16x16x32_bf16 v[28:31], v[56:59], v[2:5], v[30:33]
	s_nop 7
	v_pk_mul_f32 v[30:31], v[30:31], s[36:37] op_sel_hi:[1,0]
	v_pk_mul_f32 v[40:41], v[28:29], s[36:37] op_sel_hi:[1,0]
	v_max_f32_e32 v28, v30, v31
	v_max3_f32 v28, v40, v41, v28
	v_max3_f32 v11, v11, v34, v28
	ds_read_b128 v[32:35], v131 offset:30720
	ds_read_b128 v[36:39], v131 offset:30784
	ds_read_b128 v[44:47], v131 offset:33024
	ds_read_b128 v[48:51], v131 offset:33088
	ds_read_b128 v[52:55], v131 offset:35328
	ds_read_b128 v[56:59], v131 offset:35392
	ds_read_b128 v[60:63], v131 offset:37632
	ds_read_b128 v[68:71], v131 offset:37696
	s_waitcnt lgkmcnt(7)
	v_mfma_f32_16x16x32_bf16 v[32:35], v[32:35], v[6:9], 0
	s_waitcnt lgkmcnt(6)
	v_mfma_f32_16x16x32_bf16 v[32:35], v[36:39], v[2:5], v[32:35]
	s_waitcnt lgkmcnt(5)
	v_mfma_f32_16x16x32_bf16 v[36:39], v[44:47], v[6:9], 0
	s_waitcnt lgkmcnt(3)
	v_mfma_f32_16x16x32_bf16 v[44:47], v[52:55], v[6:9], 0
	s_nop 3
	v_mul_f32_e64 v66, v34, s36
	v_mul_f32_e64 v67, v35, s36
	v_pk_mul_f32 v[178:179], v[32:33], s[36:37] op_sel_hi:[1,0]
	v_max_f32_e32 v28, v66, v67
	v_mfma_f32_16x16x32_bf16 v[34:37], v[48:51], v[2:5], v[36:39]
	s_nop 2
	v_max3_f32 v38, v178, v179, v28
	s_nop 3
	v_pk_mul_f32 v[64:65], v[34:35], s[36:37] op_sel_hi:[1,0]
	s_waitcnt lgkmcnt(2)
	v_mfma_f32_16x16x32_bf16 v[32:35], v[56:59], v[2:5], v[44:47]
	v_mul_f32_e64 v28, v36, s36
	v_mul_f32_e64 v29, v37, s36
	v_max_f32_e32 v36, v28, v29
	v_max3_f32 v36, v64, v65, v36
	v_max3_f32 v11, v11, v38, v36
	s_nop 2
	v_pk_mul_f32 v[54:55], v[34:35], s[36:37] op_sel_hi:[1,0]
	s_waitcnt lgkmcnt(1)
	v_mfma_f32_16x16x32_bf16 v[34:37], v[60:63], v[6:9], 0
	v_mul_f32_e64 v62, v32, s36
	v_mul_f32_e64 v63, v33, s36
	v_max_f32_e32 v32, v54, v55
	v_max3_f32 v38, v62, v63, v32
	s_waitcnt lgkmcnt(0)
	v_mfma_f32_16x16x32_bf16 v[34:37], v[68:71], v[2:5], v[34:37]
	s_nop 7
	v_pk_mul_f32 v[32:33], v[36:37], s[36:37] op_sel_hi:[1,0]
	v_pk_mul_f32 v[58:59], v[34:35], s[36:37] op_sel_hi:[1,0]
	v_max_f32_e32 v34, v32, v33
	v_max3_f32 v34, v58, v59, v34
	v_max3_f32 v11, v11, v38, v34
	ds_read_b128 v[34:37], v131 offset:39936
	ds_read_b128 v[44:47], v131 offset:40000
	ds_read_b128 v[48:51], v131 offset:42240
	ds_read_b128 v[68:71], v131 offset:42304
	ds_read_b128 v[72:75], v131 offset:44544
	ds_read_b128 v[96:99], v131 offset:44608
	ds_read_b128 v[100:103], v131 offset:46848
	ds_read_b128 v[136:139], v131 offset:46912
	s_waitcnt lgkmcnt(7)
	v_mfma_f32_16x16x32_bf16 v[34:37], v[34:37], v[6:9], 0
	s_waitcnt lgkmcnt(6)
	v_mfma_f32_16x16x32_bf16 v[34:37], v[44:47], v[2:5], v[34:37]
	s_waitcnt lgkmcnt(5)
; __device__ __forceinline__ unsigned pk2(float lo, float hi) { return pg8::cvt_pk_bf16(lo, hi); }
; #define EX2(x) __builtin_amdgcn_exp2f(x)
; template <int MODE> ...
;     ...
;             mx = fmaxf(mx, fmaxf(fmaxf(acc[0], acc[1]), fmaxf(acc[2], acc[3])));
;         }
;         __builtin_amdgcn_sched_barrier(0);
;     }
;     mx = fmaxf(mx, __shfl_xor(mx, 16)); mx = fmaxf(mx, __shfl_xor(mx, 32));
;     const float m_new = fmaxf(m_run, mx), alpha = EX2(m_run - m_new);
;     float lsum = 0.f; unsigned pkd[16][2];
; #pragma unroll
;     for (int kb = 0; kb < 16; ++kb) { const float p0 = EX2(s[kb][0] - m_new), p1 = EX2(s[kb][1] - m_new), p2 = EX2(s[kb][2] - m_new), p3 = EX2(s[kb][3] - m_new);
;         lsum += (p0 + p1) + (p2 + p3); pkd[kb][0] = pk2(p0, p1); pkd[kb][1] = pk2(p2, p3); }
	v_mfma_f32_16x16x32_bf16 v[44:47], v[48:51], v[6:9], 0
	s_nop 5
	v_mul_f32_e64 v50, v36, s36
	v_mul_f32_e64 v51, v37, s36
	s_waitcnt lgkmcnt(4)
	v_mfma_f32_16x16x32_bf16 v[36:39], v[68:71], v[2:5], v[44:47]
	v_mul_f32_e64 v60, v34, s36
	v_mul_f32_e64 v61, v35, s36
	v_max_f32_e32 v34, v50, v51
	v_max3_f32 v52, v60, v61, v34
	s_waitcnt lgkmcnt(3)
	v_mfma_f32_16x16x32_bf16 v[44:47], v[72:75], v[6:9], 0
	s_waitcnt lgkmcnt(1)
	v_mfma_f32_16x16x32_bf16 v[6:9], v[100:103], v[6:9], 0
	v_mul_f32_e64 v56, v36, s36
	v_mul_f32_e64 v57, v37, s36
	v_pk_mul_f32 v[48:49], v[38:39], s[36:37] op_sel_hi:[1,0]
	v_mfma_f32_16x16x32_bf16 v[34:37], v[96:99], v[2:5], v[44:47]
	v_max_f32_e32 v38, v48, v49
	v_max3_f32 v38, v56, v57, v38
	v_max3_f32 v11, v11, v52, v38
	s_waitcnt lgkmcnt(0)
	v_mfma_f32_16x16x32_bf16 v[2:5], v[136:139], v[2:5], v[6:9]
	s_nop 2
	v_mul_f32_e64 v46, v36, s36
	v_mul_f32_e64 v47, v37, s36
	v_pk_mul_f32 v[52:53], v[34:35], s[36:37] op_sel_hi:[1,0]
	v_max_f32_e32 v34, v46, v47
	v_max3_f32 v36, v52, v53, v34
	v_pk_mul_f32 v[34:35], v[4:5], s[36:37] op_sel_hi:[1,0]
	v_pk_mul_f32 v[44:45], v[2:3], s[36:37] op_sel_hi:[1,0]
	v_max_f32_e32 v2, v34, v35
	v_max3_f32 v2, v44, v45, v2
	v_max3_f32 v2, v11, v36, v2
	ds_bpermute_b32 v3, v119, v2
	v_mov_b32_e32 v69, v1
	v_add_u32_e32 v100, 0xe000, v132
	v_add_u32_e32 v101, 0xc000, v133
	v_add_u32_e32 v102, 0xc000, v134
	s_waitcnt lgkmcnt(0)
	v_max_f32_e32 v3, v3, v3
	v_max_f32_e32 v2, v2, v3
	ds_bpermute_b32 v3, v120, v2
	s_waitcnt lgkmcnt(0)
	v_max3_f32 v11, v81, v2, v3
	v_sub_f32_e32 v2, v140, v11
	v_sub_f32_e32 v3, v141, v11
	v_sub_f32_e32 v5, v76, v11
	v_sub_f32_e32 v6, v77, v11
	v_exp_f32_e32 v2, v2
	v_exp_f32_e32 v4, v3
	v_exp_f32_e32 v3, v5
	v_exp_f32_e32 v5, v6
	v_sub_f32_e32 v7, v144, v11
	v_sub_f32_e32 v6, v145, v11
	v_exp_f32_e32 v8, v7
	v_exp_f32_e32 v9, v6
	v_pk_add_f32 v[6:7], v[2:3], v[4:5]
	v_sub_f32_e32 v40, v40, v11
	v_pk_add_f32 v[38:39], v[6:7], v[6:7] op_sel_hi:[0,1]
	v_sub_f32_e32 v6, v142, v11
	v_exp_f32_e32 v36, v6
	v_sub_f32_e32 v6, v143, v11
	v_cvt_pk_bf16_f32 v7, v3, v5
	v_add_f32_e32 v3, v8, v9
	v_cvt_pk_bf16_f32 v8, v8, v9
	v_sub_f32_e32 v9, v146, v11
	v_exp_f32_e32 v37, v6
	v_cvt_pk_bf16_f32 v6, v2, v4
	v_sub_f32_e32 v2, v148, v11
	v_sub_f32_e32 v4, v149, v11
	v_exp_f32_e32 v38, v9
	v_sub_f32_e32 v9, v147, v11
	v_exp_f32_e32 v2, v2
	v_exp_f32_e32 v4, v4
	v_exp_f32_e32 v68, v9
	v_add_f32_e32 v5, v36, v37
	v_cvt_pk_bf16_f32 v9, v36, v37
	v_pk_add_f32 v[36:37], v[2:3], v[4:5]
	v_pk_add_f32 v[70:71], v[38:39], v[68:69]
	v_sub_f32_e32 v3, v152, v11
	v_pk_add_f32 v[36:37], v[36:37], v[70:71]
	v_exp_f32_e32 v70, v3
	v_sub_f32_e32 v3, v153, v11
	v_exp_f32_e32 v72, v3
	v_sub_f32_e32 v3, v150, v11
	v_exp_f32_e32 v71, v3
	v_sub_f32_e32 v3, v151, v11
	v_exp_f32_e32 v73, v3
	v_pk_add_f32 v[74:75], v[36:37], v[36:37] op_sel_hi:[0,1]
	v_cvt_pk_bf16_f32 v36, v2, v4
	v_cvt_pk_bf16_f32 v37, v38, v68
	v_pk_add_f32 v[2:3], v[70:71], v[72:73]
	v_sub_f32_e32 v4, v154, v11
	v_pk_add_f32 v[68:69], v[2:3], v[2:3] op_sel_hi:[0,1]
	v_sub_f32_e32 v2, v156, v11
	v_sub_f32_e32 v3, v157, v11
	v_exp_f32_e32 v76, v4
	v_sub_f32_e32 v4, v155, v11
	v_sub_f32_e32 v68, v161, v11
	v_exp_f32_e32 v2, v2
	v_exp_f32_e32 v3, v3
	v_exp_f32_e32 v77, v4
	v_cvt_pk_bf16_f32 v38, v70, v72
	v_sub_f32_e32 v4, v160, v11
	v_exp_f32_e32 v70, v68
	v_sub_f32_e32 v68, v158, v11
	v_sub_f32_e32 v72, v159, v11
	v_exp_f32_e32 v4, v4
	v_exp_f32_e32 v68, v68
	v_exp_f32_e32 v74, v72
	v_cvt_pk_bf16_f32 v39, v71, v73
	v_add_f32_e32 v5, v2, v3
	v_add_f32_e32 v71, v76, v77
	v_cvt_pk_bf16_f32 v2, v2, v3
	v_cvt_pk_bf16_f32 v3, v76, v77
	v_pk_add_f32 v[72:73], v[4:5], v[70:71]
	v_pk_add_f32 v[76:77], v[68:69], v[74:75]
	v_sub_f32_e32 v5, v176, v11
	v_pk_add_f32 v[72:73], v[72:73], v[76:77]
	v_exp_f32_e32 v76, v5
	v_sub_f32_e32 v5, v177, v11
	v_exp_f32_e32 v96, v5
	v_sub_f32_e32 v5, v42, v11
	v_exp_f32_e32 v77, v5
	v_sub_f32_e32 v5, v43, v11
	v_exp_f32_e32 v97, v5
	v_sub_f32_e32 v30, v30, v11
	v_cvt_pk_bf16_f32 v5, v68, v74
	v_exp_f32_e32 v74, v30
	v_pk_add_f32 v[42:43], v[76:77], v[96:97]
	v_sub_f32_e32 v30, v31, v11
	v_pk_add_f32 v[68:69], v[42:43], v[42:43] op_sel_hi:[0,1]
	v_exp_f32_e32 v42, v40
	v_sub_f32_e32 v40, v41, v11
	v_exp_f32_e32 v43, v40
	v_exp_f32_e32 v75, v30
	v_sub_f32_e32 v30, v178, v11
	v_sub_f32_e32 v68, v179, v11
	v_sub_f32_e32 v66, v66, v11
	v_pk_add_f32 v[72:73], v[72:73], v[72:73] op_sel_hi:[0,1]
	v_cvt_pk_bf16_f32 v4, v4, v70
	v_exp_f32_e32 v30, v30
	v_exp_f32_e32 v70, v68
	v_exp_f32_e32 v68, v66
	v_sub_f32_e32 v66, v67, v11
	v_exp_f32_e32 v72, v66
	v_add_f32_e32 v31, v42, v43
	v_add_f32_e32 v71, v74, v75
	v_pk_add_f32 v[66:67], v[30:31], v[70:71]
	v_sub_f32_e32 v31, v64, v11
	v_sub_f32_e32 v28, v28, v11
	v_cvt_pk_bf16_f32 v42, v42, v43
	v_cvt_pk_bf16_f32 v43, v74, v75
	v_pk_add_f32 v[74:75], v[68:69], v[72:73]
	v_exp_f32_e32 v64, v31
	v_sub_f32_e32 v31, v65, v11
	v_exp_f32_e32 v65, v28
	v_sub_f32_e32 v28, v29, v11
	v_pk_add_f32 v[66:67], v[66:67], v[74:75]
	v_exp_f32_e32 v74, v31
	v_exp_f32_e32 v75, v28
	v_cvt_pk_bf16_f32 v28, v30, v70
	v_sub_f32_e32 v54, v54, v11
	v_cvt_pk_bf16_f32 v29, v68, v72
	v_pk_add_f32 v[30:31], v[64:65], v[74:75]
	v_sub_f32_e32 v62, v62, v11
	v_pk_add_f32 v[68:69], v[30:31], v[30:31] op_sel_hi:[0,1]
	v_cvt_pk_bf16_f32 v30, v64, v74
	v_sub_f32_e32 v63, v63, v11
	v_exp_f32_e32 v74, v54
	v_sub_f32_e32 v54, v55, v11
	v_sub_f32_e32 v32, v32, v11
	v_pk_add_f32 v[66:67], v[66:67], v[66:67] op_sel_hi:[0,1]
	v_cvt_pk_bf16_f32 v31, v65, v75
	v_exp_f32_e32 v62, v62
	v_exp_f32_e32 v63, v63
	v_exp_f32_e32 v75, v54
	v_sub_f32_e32 v54, v58, v11
	v_sub_f32_e32 v58, v59, v11
	v_exp_f32_e32 v68, v32
; __device__ __forceinline__ unsigned pk2(float lo, float hi) { return pg8::cvt_pk_bf16(lo, hi); }
; #define EX2(x) __builtin_amdgcn_exp2f(x)
; template <int MODE> ...
;     ...
;     const float m_new = fmaxf(m_run, mx), alpha = EX2(m_run - m_new);
;     float lsum = 0.f; unsigned pkd[16][2];
; #pragma unroll
;     for (int kb = 0; kb < 16; ++kb) { const float p0 = EX2(s[kb][0] - m_new), p1 = EX2(s[kb][1] - m_new), p2 = EX2(s[kb][2] - m_new), p3 = EX2(s[kb][3] - m_new);
;         lsum += (p0 + p1) + (p2 + p3); pkd[kb][0] = pk2(p0, p1); pkd[kb][1] = pk2(p2, p3); }
;     lsum += __shfl_xor(lsum, 16); lsum += __shfl_xor(lsum, 32);
;     l_run = l_run * alpha + lsum; m_run = m_new;
; #pragma unroll
;     for (int db = 0; db < 4; ++db) O[db] = O[db] * alpha;
; #pragma unroll
;     for (int pg = 0; pg < 4; ++pg) {
;         u32x2 vlo[2][4], vhi[2][4];
; #pragma unroll
;         for (int i = 0; i < 2; ++i) { const int pr = pg * 2 + i;
;             const int posA = MODE == 0 ? ((rs + pr) * 64 + kc0 + fq * 4) : (SEQ + pr * 32 + fq * 4);
; #pragma unroll
;             for (int db = 0; db < 4; ++db) {
;                 if (MODE == 2) { const bf16_t* vp = Vc + (db * 16 + fr) * 264 + pr * 32 + fq * 4; vlo[i][db] = *(const u32x2*)vp; vhi[i][db] = *(const u32x2*)(vp + 16); }
;                 else { const bf16_t* vp = vt + (size_t)(db * 16) * VTW + posA; vlo[i][db] = *(const u32x2*)vp; vhi[i][db] = *(const u32x2*)(vp + 16); } } }
;         __builtin_amdgcn_sched_barrier(0);
; #pragma unroll
;         for (int i = 0; i < 2; ++i) { const int pr = pg * 2 + i;
;             u32x4 bw; bw.x = pkd[2 * pr][0]; bw.y = pkd[2 * pr][1]; bw.z = pkd[2 * pr + 1][0]; bw.w = pkd[2 * pr + 1][1];
;             const bf16x8 bp = as_bf16x8(bw);
; #pragma unroll
;             for (int db = 0; db < 4; ++db) { u32x4 aw; aw.x = vlo[i][db].x; aw.y = vlo[i][db].y; aw.z = vhi[i][db].x; aw.w = vhi[i][db].y;
;                 O[db] = __builtin_amdgcn_mfma_f32_16x16x32_bf16(as_bf16x8(aw), bp, O[db], 0, 0, 0); } }
	v_sub_f32_e32 v32, v33, v11
	v_exp_f32_e32 v54, v54
	v_exp_f32_e32 v58, v58
	v_exp_f32_e32 v66, v32
	v_add_f32_e32 v55, v62, v63
	v_add_f32_e32 v59, v74, v75
	v_sub_f32_e32 v33, v60, v11
	v_cvt_pk_bf16_f32 v32, v62, v63
	v_pk_add_f32 v[62:63], v[54:55], v[58:59]
	v_pk_add_f32 v[64:65], v[68:69], v[66:67]
	v_exp_f32_e32 v60, v33
	v_sub_f32_e32 v33, v61, v11
	v_pk_add_f32 v[62:63], v[62:63], v[64:65]
	v_exp_f32_e32 v64, v33
	v_sub_f32_e32 v33, v50, v11
	v_exp_f32_e32 v61, v33
	v_sub_f32_e32 v33, v51, v11
	v_exp_f32_e32 v65, v33
	v_sub_f32_e32 v33, v56, v11
	v_exp_f32_e32 v50, v33
	v_sub_f32_e32 v33, v57, v11
	v_exp_f32_e32 v51, v33
	v_sub_f32_e32 v33, v48, v11
	v_exp_f32_e32 v55, v33
	v_sub_f32_e32 v33, v49, v11
	v_exp_f32_e32 v59, v33
	v_sub_f32_e32 v33, v52, v11
	v_pk_add_f32 v[48:49], v[60:61], v[64:65]
	v_exp_f32_e32 v70, v33
	v_sub_f32_e32 v33, v53, v11
	v_pk_add_f32 v[56:57], v[48:49], v[48:49] op_sel_hi:[0,1]
	v_exp_f32_e32 v72, v33
	v_sub_f32_e32 v33, v46, v11
	v_pk_add_f32 v[62:63], v[62:63], v[62:63] op_sel_hi:[0,1]
	v_exp_f32_e32 v56, v33
	v_sub_f32_e32 v33, v47, v11
	v_exp_f32_e32 v62, v33
	v_sub_f32_e32 v33, v44, v11
	v_exp_f32_e32 v52, v33
	v_sub_f32_e32 v33, v45, v11
	v_exp_f32_e32 v53, v33
	v_sub_f32_e32 v81, v81, v11
	v_sub_f32_e32 v33, v34, v11
	v_sub_f32_e32 v11, v35, v11
	v_pk_add_f32 v[34:35], v[94:95], v[94:95] op_sel:[0,1] op_sel_hi:[1,0]
	v_pk_add_f32 v[44:45], v[92:93], v[92:93] op_sel:[0,1] op_sel_hi:[1,0]
	v_mov_b32_e32 v35, v52
	v_mov_b32_e32 v45, v53
	v_pk_add_f32 v[34:35], v[34:35], v[44:45]
	v_exp_f32_e32 v67, v33
	v_exp_f32_e32 v69, v11
	ds_bpermute_b32 v44, v119, v34
	v_add_f32_e32 v71, v50, v51
	v_add_f32_e32 v73, v55, v59
	v_pk_add_f32 v[46:47], v[70:71], v[72:73]
	v_pk_add_f32 v[48:49], v[56:57], v[62:63]
	v_add_f32_e32 v45, v67, v69
	v_pk_add_f32 v[46:47], v[46:47], v[48:49]
	s_waitcnt lgkmcnt(0)
	v_pk_add_f32 v[44:45], v[34:35], v[44:45]
	v_pk_add_f32 v[46:47], v[46:47], v[46:47] op_sel_hi:[0,1]
	ds_bpermute_b32 v46, v120, v44
	v_cvt_pk_bf16_f32 v34, v54, v58
	v_cvt_pk_bf16_f32 v40, v76, v96
	v_exp_f32_e32 v76, v81
	v_add_u32_e32 v81, 0xc000, v132
	s_waitcnt lgkmcnt(0)
	v_pk_add_f32 v[46:47], v[44:45], v[46:47]
	ds_bpermute_b32 v11, v119, v47
	v_cvt_pk_bf16_f32 v41, v77, v97
	v_cvt_pk_bf16_f32 v33, v74, v75
	v_cvt_pk_bf16_f32 v35, v68, v66
	v_cvt_pk_bf16_f32 v48, v60, v64
	s_waitcnt lgkmcnt(0)
	v_pk_add_f32 v[10:11], v[46:47], v[10:11]
	ds_bpermute_b32 v54, v120, v11
	v_cvt_pk_bf16_f32 v49, v61, v65
	v_cvt_pk_bf16_f32 v50, v50, v51
	v_cvt_pk_bf16_f32 v51, v55, v59
	v_cvt_pk_bf16_f32 v44, v70, v72
	v_cvt_pk_bf16_f32 v45, v56, v62
	v_cvt_pk_bf16_f32 v46, v52, v53
	v_cvt_pk_bf16_f32 v47, v67, v69
	s_waitcnt lgkmcnt(0)
	v_add_f32_e32 v77, v11, v54
	ds_read2_b64 v[52:55], v81 offset1:4
	ds_read2_b64 v[56:59], v100 offset0:32 offset1:36
	ds_read2_b64 v[60:63], v101 offset1:4
	ds_read2_b64 v[64:67], v102 offset1:4
	ds_read2_b64 v[68:71], v81 offset0:8 offset1:12
	ds_read2_b64 v[72:75], v100 offset0:40 offset1:44
	ds_read2_b64 v[92:95], v101 offset0:8 offset1:12
	ds_read2_b64 v[96:99], v102 offset0:8 offset1:12
	v_fmac_f32_e32 v77, v10, v76
	v_pk_mul_f32 v[26:27], v[26:27], v[76:77] op_sel_hi:[1,0]
	v_pk_mul_f32 v[24:25], v[24:25], v[76:77] op_sel_hi:[1,0]
	v_pk_mul_f32 v[22:23], v[22:23], v[76:77] op_sel_hi:[1,0]
	v_pk_mul_f32 v[20:21], v[20:21], v[76:77] op_sel_hi:[1,0]
	v_pk_mul_f32 v[14:15], v[14:15], v[76:77] op_sel_hi:[1,0]
	v_pk_mul_f32 v[12:13], v[12:13], v[76:77] op_sel_hi:[1,0]
	v_pk_mul_f32 v[18:19], v[18:19], v[76:77] op_sel_hi:[1,0]
	v_pk_mul_f32 v[16:17], v[16:17], v[76:77] op_sel_hi:[1,0]
	s_waitcnt lgkmcnt(7)
	v_mfma_f32_16x16x32_bf16 v[24:27], v[52:55], v[6:9], v[24:27]
	s_waitcnt lgkmcnt(6)
	v_mfma_f32_16x16x32_bf16 v[20:23], v[56:59], v[6:9], v[20:23]
	s_waitcnt lgkmcnt(5)
	v_mfma_f32_16x16x32_bf16 v[10:13], v[60:63], v[6:9], v[12:15]
	s_waitcnt lgkmcnt(4)
	v_mfma_f32_16x16x32_bf16 v[6:9], v[64:67], v[6:9], v[16:19]
	s_waitcnt lgkmcnt(3)
	v_mfma_f32_16x16x32_bf16 v[14:17], v[68:71], v[36:39], v[24:27]
	s_waitcnt lgkmcnt(2)
	v_mfma_f32_16x16x32_bf16 v[18:21], v[72:75], v[36:39], v[20:23]
	s_waitcnt lgkmcnt(1)
	v_mfma_f32_16x16x32_bf16 v[10:13], v[92:95], v[36:39], v[10:13]
	s_waitcnt lgkmcnt(0)
	v_mfma_f32_16x16x32_bf16 v[6:9], v[96:99], v[36:39], v[6:9]
	ds_read2_b64 v[22:25], v81 offset0:16 offset1:20
	ds_read2_b64 v[36:39], v100 offset0:48 offset1:52
	ds_read2_b64 v[52:55], v101 offset0:16 offset1:20
	ds_read2_b64 v[56:59], v102 offset0:16 offset1:20
	ds_read2_b64 v[60:63], v81 offset0:24 offset1:28
	ds_read2_b64 v[64:67], v100 offset0:56 offset1:60
	ds_read2_b64 v[68:71], v101 offset0:24 offset1:28
	ds_read2_b64 v[72:75], v102 offset0:24 offset1:28
	s_waitcnt lgkmcnt(7)
	v_mfma_f32_16x16x32_bf16 v[14:17], v[22:25], v[2:5], v[14:17]
	s_waitcnt lgkmcnt(6)
	v_mfma_f32_16x16x32_bf16 v[18:21], v[36:39], v[2:5], v[18:21]
	s_waitcnt lgkmcnt(5)
	v_mfma_f32_16x16x32_bf16 v[10:13], v[52:55], v[2:5], v[10:13]
	s_waitcnt lgkmcnt(4)
	v_mfma_f32_16x16x32_bf16 v[2:5], v[56:59], v[2:5], v[6:9]
	s_waitcnt lgkmcnt(3)
	v_mfma_f32_16x16x32_bf16 v[6:9], v[60:63], v[40:43], v[14:17]
	s_waitcnt lgkmcnt(2)
	v_mfma_f32_16x16x32_bf16 v[14:17], v[64:67], v[40:43], v[18:21]
	s_waitcnt lgkmcnt(1)
	v_mfma_f32_16x16x32_bf16 v[10:13], v[68:71], v[40:43], v[10:13]
	s_waitcnt lgkmcnt(0)
	v_mfma_f32_16x16x32_bf16 v[2:5], v[72:75], v[40:43], v[2:5]
	ds_read2_b64 v[18:21], v81 offset0:32 offset1:36
	ds_read2_b64 v[22:25], v100 offset0:64 offset1:68
	ds_read2_b64 v[36:39], v101 offset0:32 offset1:36
	ds_read2_b64 v[40:43], v102 offset0:32 offset1:36
	ds_read2_b64 v[52:55], v81 offset0:40 offset1:44
	ds_read2_b64 v[56:59], v100 offset0:72 offset1:76
	ds_read2_b64 v[60:63], v101 offset0:40 offset1:44
	ds_read2_b64 v[64:67], v102 offset0:40 offset1:44
	s_waitcnt lgkmcnt(7)
; __device__ __forceinline__ unsigned pk2(float lo, float hi) { return pg8::cvt_pk_bf16(lo, hi); }
; template <int MODE> ...
;     ...
;                 O[db] = __builtin_amdgcn_mfma_f32_16x16x32_bf16(as_bf16x8(aw), bp, O[db], 0, 0, 0); } }
;         __builtin_amdgcn_sched_barrier(0);
;     }
; }
; template <bool CTXLDS>
; __device__ __forceinline__ void na_tile(const bf16_t* U, const bf16_t* VT, bf16_t* MIX, const float* rpbL, const bf16_t* Kc, const bf16_t* Vc, bool lat, int b, int r, int c0, int qrow0, int h, int lane) {
;     const int fr = lane & 15, fq = lane >> 4;
;     const bf16_t* qp = U + (size_t)(qrow0 + fr) * INP + NQ0 + h * 64 + fq * 8;
;     const bf16x8 bq0 = as_bf16x8(*(const u32x4*)qp), bq1 = as_bf16x8(*(const u32x4*)(qp + 32));
;     float m_run = -1e30f, l_run = 0.f;
;     f32x4 O[4];
; #pragma unroll
;     for (int db = 0; db < 4; ++db) O[db] = (f32x4){0.f, 0.f, 0.f, 0.f};
;     const bf16_t* vt = VT + (size_t)((b * 6 + h) * 64 + fr) * VTW;
;     const int rs = min(max(r - 4, 0), 120), kc0 = min(max(c0 - 8, 0), 32);
;     const int qcol = c0 + fr, cs = min(max(qcol - 8, 0), 48);
;     if (lat) na_chunk<0>(U, vt, rpbL, Kc, Vc, b, r, h, rs, kc0, qcol, cs, bq0, bq1, m_run, l_run, O, fr, fq);
;     na_chunk<CTXLDS ? 2 : 1>(U, vt, rpbL, Kc, Vc, b, r, h, rs, kc0, qcol, cs, bq0, bq1, m_run, l_run, O, fr, fq);
;     const float inv = 1.f / l_run;
;     bf16_t* op = MIX + (size_t)(qrow0 + fr) * DM + 640 + h * 64 + fq * 4;
; #pragma unroll
;     for (int db = 0; db < 4; ++db) { u32x2 w; w.x = pk2(O[db][0] * inv, O[db][1] * inv); w.y = pk2(O[db][2] * inv, O[db][3] * inv); *(u32x2*)(op + db * 16) = w; }
; __device__ __forceinline__ void na_phase(ParamsK p, int l, unsigned char* smem, bool with_ctx) {
;     ...
;         for (int round = 0; round < NL / 256; ++round) {
	v_mfma_f32_16x16x32_bf16 v[6:9], v[18:21], v[28:31], v[6:9]
	s_waitcnt lgkmcnt(6)
	v_mfma_f32_16x16x32_bf16 v[14:17], v[22:25], v[28:31], v[14:17]
	s_waitcnt lgkmcnt(5)
	v_mfma_f32_16x16x32_bf16 v[10:13], v[36:39], v[28:31], v[10:13]
	s_waitcnt lgkmcnt(4)
	v_mfma_f32_16x16x32_bf16 v[2:5], v[40:43], v[28:31], v[2:5]
	s_waitcnt lgkmcnt(3)
	v_mfma_f32_16x16x32_bf16 v[6:9], v[52:55], v[32:35], v[6:9]
	s_waitcnt lgkmcnt(2)
	v_mfma_f32_16x16x32_bf16 v[14:17], v[56:59], v[32:35], v[14:17]
	s_waitcnt lgkmcnt(1)
	v_mfma_f32_16x16x32_bf16 v[10:13], v[60:63], v[32:35], v[10:13]
	s_waitcnt lgkmcnt(0)
	v_mfma_f32_16x16x32_bf16 v[2:5], v[64:67], v[32:35], v[2:5]
	ds_read2_b64 v[18:21], v81 offset0:48 offset1:52
	ds_read2_b64 v[22:25], v100 offset0:80 offset1:84
	ds_read2_b64 v[26:29], v101 offset0:48 offset1:52
	ds_read2_b64 v[30:33], v102 offset0:48 offset1:52
	ds_read2_b64 v[34:37], v81 offset0:56 offset1:60
	ds_read2_b64 v[38:41], v100 offset0:88 offset1:92
	ds_read2_b64 v[52:55], v101 offset0:56 offset1:60
	ds_read2_b64 v[56:59], v102 offset0:56 offset1:60
	s_waitcnt lgkmcnt(7)
	v_mfma_f32_16x16x32_bf16 v[6:9], v[18:21], v[48:51], v[6:9]
	s_waitcnt lgkmcnt(6)
	v_mfma_f32_16x16x32_bf16 v[14:17], v[22:25], v[48:51], v[14:17]
	s_waitcnt lgkmcnt(5)
	v_mfma_f32_16x16x32_bf16 v[10:13], v[26:29], v[48:51], v[10:13]
	s_waitcnt lgkmcnt(4)
	v_mfma_f32_16x16x32_bf16 v[2:5], v[30:33], v[48:51], v[2:5]
	s_waitcnt lgkmcnt(3)
	v_mfma_f32_16x16x32_bf16 v[6:9], v[34:37], v[44:47], v[6:9]
	s_waitcnt lgkmcnt(2)
	v_mfma_f32_16x16x32_bf16 v[14:17], v[38:41], v[44:47], v[14:17]
	s_waitcnt lgkmcnt(1)
	v_mfma_f32_16x16x32_bf16 v[10:13], v[52:55], v[44:47], v[10:13]
	s_waitcnt lgkmcnt(0)
	v_mfma_f32_16x16x32_bf16 v[2:5], v[56:59], v[44:47], v[2:5]
	v_div_scale_f32 v18, s[2:3], v77, v77, 1.0
	v_rcp_f32_e32 v19, v18
	v_div_scale_f32 v20, vcc, 1.0, v77, 1.0
	s_addk_i32 s22, 0x100
	v_fma_f32 v21, -v18, v19, 1.0
	v_fmac_f32_e32 v19, v21, v19
	v_mul_f32_e32 v21, v20, v19
	v_fma_f32 v22, -v18, v21, v20
	v_fmac_f32_e32 v21, v22, v19
	v_fma_f32 v18, -v18, v21, v20
	v_div_fmas_f32 v18, v18, v19, v21
	v_lshlrev_b64 v[20:21], 11, v[84:85]
	v_div_fixup_f32 v18, v18, v77, 1.0
	v_lshl_add_u64 v[20:21], s[42:43], 0, v[20:21]
	v_lshl_add_u64 v[20:21], s[60:61], 1, v[20:21]
	v_pk_mul_f32 v[6:7], v[18:19], v[6:7] op_sel_hi:[0,1]
	v_pk_mul_f32 v[8:9], v[18:19], v[8:9] op_sel_hi:[0,1]
	v_lshl_add_u64 v[20:21], v[78:79], 1, v[20:21]
	v_cvt_pk_bf16_f32 v6, v6, v7
	v_cvt_pk_bf16_f32 v7, v8, v9
	global_store_dwordx2 v[20:21], v[6:7], off offset:1280
	v_pk_mul_f32 v[6:7], v[18:19], v[14:15] op_sel_hi:[0,1]
	v_pk_mul_f32 v[8:9], v[18:19], v[16:17] op_sel_hi:[0,1]
	v_cvt_pk_bf16_f32 v6, v6, v7
	v_cvt_pk_bf16_f32 v7, v8, v9
	global_store_dwordx2 v[20:21], v[6:7], off offset:1312
	v_pk_mul_f32 v[6:7], v[18:19], v[10:11] op_sel_hi:[0,1]
	v_pk_mul_f32 v[8:9], v[18:19], v[12:13] op_sel_hi:[0,1]
	v_pk_mul_f32 v[2:3], v[18:19], v[2:3] op_sel_hi:[0,1]
	v_pk_mul_f32 v[4:5], v[18:19], v[4:5] op_sel_hi:[0,1]
	v_cvt_pk_bf16_f32 v6, v6, v7
	v_cvt_pk_bf16_f32 v7, v8, v9
	v_cvt_pk_bf16_f32 v2, v2, v3
	v_cvt_pk_bf16_f32 v3, v4, v5
	s_cmpk_eq_i32 s22, 0xc00
	global_store_dwordx2 v[20:21], v[6:7], off offset:1344
	global_store_dwordx2 v[20:21], v[2:3], off offset:1376
	s_cbranch_scc1 .LBB0_691
; __device__ __forceinline__ void na_phase(ParamsK p, int l, unsigned char* smem, bool with_ctx) {
;     ...
;         for (int round = 0; round < NL / 256; ++round) {
;             const int w = lw + 256 * round, cq = w & 3, rr = (w >> 2) & 1, h = (w >> 3) % 6, r = (w / 48) * 2 + rr;
;             __syncthreads();
; #pragma unroll
;             for (int i = 0; i < 4; ++i) { const int idx = i * 512 + tid, key = idx >> 3, part = idx & 7;
;                 *(u32x4*)(Kc + key * 72 + part * 8) = *(const u32x4*)(U + (size_t)(TL + b * CTXL + key) * INP + NK0 + h * 64 + part * 8); }
; #pragma unroll
;             for (int i = 0; i < 4; ++i) { const int idx = i * 512 + tid, d = idx >> 5, part = idx & 31;
;                 *(u32x4*)(Vc + d * 264 + part * 8) = *(const u32x4*)(VT + (size_t)((b * 6 + h) * 64 + d) * VTW + SEQ + part * 8); }
;             __syncthreads();
;             na_tile<true>(U, VT, MIX, rpbL, Kc, Vc, true, b, r, cq * 16, b * SEQ + r * 64 + cq * 16, h, lane);
.LBB0_563:
	s_add_i32 s2, s62, s22
	s_ashr_i32 s3, s2, 3
	s_mul_hi_i32 s4, s3, 0x2aaaaaab
	s_lshr_b32 s5, s4, 31
	s_add_i32 s4, s4, s5
	s_mul_i32 s4, s4, 6
	s_sub_i32 s6, s3, s4
	s_lshl_b32 s60, s6, 6
	s_ashr_i32 s61, s60, 31
	s_lshl_b64 s[18:19], s[60:61], 1
	v_lshl_add_u64 v[2:3], v[82:83], 0, s[18:19]
	s_barrier
	global_load_dwordx4 v[2:5], v[2:3], off
	s_mul_hi_i32 s2, s2, 0x2aaaaaab
	s_lshr_b32 s3, s2, 31
	s_ashr_i32 s2, s2, 3
	s_add_i32 s2, s2, s3
	s_add_i32 s3, s6, s64
	s_lshl_b32 s3, s3, 6
	v_mov_b64_e32 v[6:7], s[44:45]
	s_lshl_b32 s2, s2, 1
	s_or_b32 s2, s2, s0
	v_lshl_add_u32 v84, s2, 6, v104
	s_mul_i32 s6, s6, 15
	v_mov_b32_e32 v11, v1
	v_mov_b32_e32 v81, v1
	s_and_b32 s97, s2, -2
	s_max_i32 s97, s97, 4
	s_add_i32 s97, s97, -4
	s_min_u32 s97, s97, 0x78
	s_max_i32 s98, s2, 4
	s_add_i32 s98, s98, -4
	s_min_u32 s98, s98, 0x78
	s_sub_i32 s98, s98, s97
	s_lshl_b32 s98, s98, 7
	v_add_u32_e32 v247, s98, v243
	v_add_u32_e32 v248, s98, v244
	v_add_u32_e32 v249, s98, v245
	v_add_u32_e32 v253, s98, v246
	s_mul_i32 s100, s3, 0x4200
	s_lshl_b32 s97, s97, 7
	s_add_u32 s100, s100, s97
	s_add_u32 s100, s44, s100
	s_addc_u32 s101, s45, 0
	global_load_dwordx4 v[180:183], v216, s[100:101]
	global_load_dwordx4 v[184:187], v217, s[100:101]
	global_load_dwordx4 v[188:191], v218, s[100:101]
	global_load_dwordx4 v[192:195], v219, s[100:101]
	global_load_dwordx4 v[196:199], v220, s[100:101]
	global_load_dwordx4 v[200:203], v221, s[100:101]
	global_load_dwordx4 v[204:207], v222, s[100:101]
	global_load_dwordx4 v[208:211], v223, s[100:101]
	global_load_dwordx4 v[212:215], v224, s[100:101]
	s_waitcnt vmcnt(0)
	ds_write_b128 v123, v[2:5] offset:12288
	v_lshl_add_u64 v[2:3], v[86:87], 0, s[18:19]
	global_load_dwordx4 v[2:5], v[2:3], off
	s_waitcnt vmcnt(0)
	ds_write_b128 v124, v[2:5] offset:12288
	v_lshl_add_u64 v[2:3], v[88:89], 0, s[18:19]
	global_load_dwordx4 v[2:5], v[2:3], off
	s_waitcnt vmcnt(0)
	ds_write_b128 v125, v[2:5] offset:12288
	v_lshl_add_u64 v[2:3], v[90:91], 0, s[18:19]
	global_load_dwordx4 v[2:5], v[2:3], off
	s_waitcnt vmcnt(0)
	ds_write_b128 v126, v[2:5] offset:12288
	v_add_u32_e32 v2, s3, v116
	v_mad_i64_i32 v[2:3], s[4:5], v2, s68, v[6:7]
	v_lshl_add_u64 v[2:3], v[2:3], 0, v[0:1]
	v_add_co_u32_e32 v2, vcc, s66, v2
	s_nop 1
	v_addc_co_u32_e32 v3, vcc, 0, v3, vcc
	global_load_dwordx4 v[2:5], v[2:3], off
	s_waitcnt vmcnt(0)
	ds_write_b128 v127, v[2:5] offset:49152
	v_add_u32_e32 v2, s3, v117
	v_mad_i64_i32 v[2:3], s[4:5], v2, s68, v[6:7]
	v_lshl_add_u64 v[2:3], v[2:3], 0, v[0:1]
	v_add_co_u32_e32 v2, vcc, s66, v2
	s_nop 1
	v_addc_co_u32_e32 v3, vcc, 0, v3, vcc
	global_load_dwordx4 v[2:5], v[2:3], off
	s_waitcnt vmcnt(0)
	ds_write_b128 v128, v[2:5] offset:49152
	v_add_u32_e32 v2, s3, v121
	v_mad_i64_i32 v[2:3], s[4:5], v2, s68, v[6:7]
	v_lshl_add_u64 v[2:3], v[2:3], 0, v[0:1]
	v_add_co_u32_e32 v2, vcc, s66, v2
	s_nop 1
	v_addc_co_u32_e32 v3, vcc, 0, v3, vcc
	global_load_dwordx4 v[2:5], v[2:3], off
	s_waitcnt vmcnt(0)
	ds_write_b128 v129, v[2:5] offset:49152
	v_add_u32_e32 v2, s3, v122
	v_mad_i64_i32 v[2:3], s[4:5], v2, s68, v[6:7]
	v_lshl_add_u64 v[2:3], v[2:3], 0, v[0:1]
	v_add_co_u32_e32 v2, vcc, s66, v2
	s_nop 1
	v_addc_co_u32_e32 v3, vcc, 0, v3, vcc
	global_load_dwordx4 v[2:5], v[2:3], off
	s_waitcnt vmcnt(0)
	ds_write_b128 v130, v[2:5] offset:49152
	ds_write_b128 v225, v[180:183]
	ds_write_b128 v226, v[184:187]
	ds_write_b128 v227, v[188:191]
	ds_write_b128 v237, v[192:195]
	ds_write_b128 v238, v[196:199]
	ds_write_b128 v239, v[200:203]
	ds_write_b128 v240, v[204:207]
	ds_write_b128 v241, v[208:211]
	ds_write_b128 v242, v[212:215]
	v_mov_b64_e32 v[2:3], s[40:41]
	v_mad_i64_i32 v[2:3], s[4:5], v84, s83, v[2:3]
	s_max_i32 s4, s2, 4
	s_add_i32 s4, s4, -4
	s_min_u32 s5, s4, 0x78
	s_sub_i32 s2, s6, s2
	s_add_i32 s4, s2, s5
	s_lshl_b32 s2, s5, 6
	v_add_u32_e32 v10, s2, v105
	v_mul_u32_u24_e32 v10, 0x1a00, v10
	v_lshl_add_u64 v[10:11], s[40:41], 0, v[10:11]
	v_lshl_add_u64 v[10:11], v[10:11], 0, s[18:19]
	v_lshl_add_u64 v[10:11], v[10:11], 0, v[80:81]
	s_mov_b64 s[6:7], 0x1240
	v_lshl_add_u64 v[2:3], v[2:3], 0, s[18:19]
	v_lshl_add_u64 v[12:13], v[10:11], 0, s[6:7]
	v_add_co_u32_e32 v10, vcc, s86, v10
	v_lshl_add_u64 v[2:3], v[2:3], 0, v[80:81]
	s_nop 0
	v_addc_co_u32_e32 v11, vcc, 0, v11, vcc
	s_waitcnt lgkmcnt(0)
	s_barrier
	global_load_dwordx4 v[6:9], v[2:3], off offset:3904
	s_nop 0
	global_load_dwordx4 v[2:5], v[2:3], off offset:3968
	s_nop 0
	global_load_dwordx4 v[34:37], v[10:11], off offset:576
	global_load_dwordx4 v[38:41], v[12:13], off offset:64
	v_add_u32_e32 v10, s2, v107
	v_mul_u32_u24_e32 v10, 0x1a00, v10
	v_mov_b32_e32 v11, v1
	v_lshl_add_u64 v[10:11], s[40:41], 0, v[10:11]
	v_lshl_add_u64 v[10:11], v[10:11], 0, s[18:19]
	v_lshl_add_u64 v[10:11], v[10:11], 0, v[80:81]
	v_lshl_add_u64 v[12:13], v[10:11], 0, s[6:7]
	v_add_co_u32_e32 v10, vcc, s86, v10
	s_add_i32 s5, s2, 64
	s_nop 0
	v_addc_co_u32_e32 v11, vcc, 0, v11, vcc
	global_load_dwordx4 v[26:29], v[10:11], off offset:576
	global_load_dwordx4 v[30:33], v[12:13], off offset:64
	v_add_u32_e32 v10, s5, v105
	v_mul_u32_u24_e32 v10, 0x1a00, v10
	v_mov_b32_e32 v11, v1
	v_lshl_add_u64 v[10:11], s[40:41], 0, v[10:11]
	v_lshl_add_u64 v[10:11], v[10:11], 0, s[18:19]
	v_lshl_add_u64 v[10:11], v[10:11], 0, v[80:81]
	v_lshl_add_u64 v[12:13], v[10:11], 0, s[6:7]
	v_add_co_u32_e32 v10, vcc, s86, v10
	s_mulk_i32 s4, 0x7c
	s_nop 0
	v_addc_co_u32_e32 v11, vcc, 0, v11, vcc
	global_load_dwordx4 v[18:21], v[10:11], off offset:576
	global_load_dwordx4 v[22:25], v[12:13], off offset:64
	v_add_u32_e32 v10, s5, v107
	v_mul_u32_u24_e32 v10, 0x1a00, v10
	v_mov_b32_e32 v11, v1
	v_lshl_add_u64 v[10:11], s[40:41], 0, v[10:11]
	v_lshl_add_u64 v[10:11], v[10:11], 0, s[18:19]
	v_lshl_add_u64 v[10:11], v[10:11], 0, v[80:81]
	v_lshl_add_u64 v[14:15], v[10:11], 0, s[6:7]
	v_add_co_u32_e32 v10, vcc, s86, v10
	s_nop 1
	v_addc_co_u32_e32 v11, vcc, 0, v11, vcc
	global_load_dwordx4 v[10:13], v[10:11], off offset:576
	s_nop 0
	global_load_dwordx4 v[14:17], v[14:15], off offset:64
	s_waitcnt vmcnt(7)
	v_mfma_f32_16x16x32_bf16 v[34:37], v[34:37], v[6:9], 0
	s_add_i32 s4, s4, 16
	s_addk_i32 s4, 0x364
	v_lshl_add_u32 v46, v108, 2, s4
	s_waitcnt vmcnt(6)
	v_mfma_f32_16x16x32_bf16 v[36:39], v[38:41], v[2:5], v[34:37]
	s_nop 7
	v_pk_mul_f32 v[34:35], v[38:39], s[36:37] op_sel_hi:[1,0]
	v_pk_mul_f32 v[36:37], v[36:37], s[36:37] op_sel_hi:[1,0]
	v_mov_b32_e32 v38, 0xf149f2ca
	v_mov_b32_e32 v39, 0xf149f2ca
	s_and_saveexec_b64 s[20:21], s[46:47]
	s_cbranch_execz .LBB0_565
	ds_read_b32 v39, v46
	s_waitcnt lgkmcnt(0)
	v_add_f32_e32 v39, v36, v39

; __device__ __forceinline__ float bflo(unsigned w) { return __uint_as_float(w << 16); }
; __device__ __forceinline__ float bfhi(unsigned w) { return __uint_as_float(w & 0xffff0000u); }
; __device__ __forceinline__ void gla_step3(ParamsK p, int l, unsigned char* smem) {
;     ...
;                 for (int db = 0; db < 4; ++db) vt[db] = as_bf16x4(*(const u32x2*)(VTG + (size_t)(bh * 64 + db * 16 + fr) * VTW + vtb + sc * 16 + fq * 4));
;                 f32x4 og[4]; u32x2 rgw[4];
;                 if (dir == 1) {
; #pragma unroll
;                     for (int db = 0; db < 4; ++db) { const u32x2 ow = *(const u32x2*)(OG + (size_t)row * 384 + h * 64 + db * 16 + fq * 4); og[db] = (f32x4){bflo(ow.x), bfhi(ow.x), bflo(ow.y), bfhi(ow.y)};
;                         rgw[db] = *(const u32x2*)(U + (size_t)row * INP + R0 + h * 64 + db * 16 + fq * 4); }
;                 }
.LBB0_815:
	s_add_i32 s0, s8, -1
	s_add_i32 s10, s9, 1
	s_and_b64 s[34:35], s[20:21], exec
	s_cselect_b32 s10, s0, s10
	s_lshl_b32 s0, s10, 5
	v_lshl_add_u64 v[66:67], v[106:107], 0, s[0:1]
	v_lshl_add_u64 v[68:69], v[66:67], 0, v[112:113]
	v_lshl_add_u64 v[70:71], v[66:67], 0, v[114:115]
	v_lshl_add_u64 v[72:73], v[66:67], 0, v[116:117]
	v_lshl_add_u64 v[66:67], v[66:67], 0, v[118:119]
	global_load_dwordx2 v[150:151], v[68:69], off
	global_load_dwordx2 v[148:149], v[70:71], off
	global_load_dwordx2 v[146:147], v[72:73], off
	global_load_dwordx2 v[144:145], v[66:67], off
	s_andn2_b64 vcc, exec, s[26:27]
	v_lshl_add_u32 v142, s10, 4, v214
	s_cbranch_vccnz .LBB0_817
	v_mad_i64_i32 v[10:11], s[34:35], v142, s84, v[108:109]
	global_load_dwordx2 v[12:13], v[10:11], off
	global_load_dwordx2 v[16:17], v[10:11], off offset:32
	global_load_dwordx2 v[20:21], v[10:11], off offset:64
	v_mad_i64_i32 v[14:15], s[34:35], v142, s83, v[120:121]
	global_load_dwordx2 v[24:25], v[10:11], off offset:96
	global_load_dwordx2 v[102:103], v[14:15], off offset:1600
	global_load_dwordx2 v[100:101], v[14:15], off offset:1632
	global_load_dwordx2 v[98:99], v[14:15], off offset:1664
	global_load_dwordx2 v[104:105], v[14:15], off offset:1696
	s_waitcnt vmcnt(13)
	s_branch .Lg3og_skip1

; template <bool NEEDQ>
; __device__ __forceinline__ void gla_stage16(const GlaRaw& R, float* qs, float* ks, float* Bs, float* Be, int tpos0, int dir, const float (&wg)[16], float bgk, int lane) {
;     ...
;         if (NEEDQ) { unpack8(R.qraw, qq);
; #pragma unroll
;             for (int i = 0; i < 8; ++i) qq[i] *= 0.17677669529663687f; }
;         if (tpos0 >= 0) { const f32x4 cs = R.cs, sn = R.sn;
; #pragma unroll
;             for (int i = 0; i < 4; ++i) { const float a = kk[2 * i] * cs[i] - kk[2 * i + 1] * sn[i], b2 = kk[2 * i] * sn[i] + kk[2 * i + 1] * cs[i]; kk[2 * i] = a; kk[2 * i + 1] = b2;
;                 if (NEEDQ) { const float c2 = qq[2 * i] * cs[i] - qq[2 * i + 1] * sn[i], d2 = qq[2 * i] * sn[i] + qq[2 * i + 1] * cs[i]; qq[2 * i] = c2; qq[2 * i + 1] = d2; } } }
;         *(f32x4*)(ks + tok * GS + qr * 8) = (f32x4){kk[0], kk[1], kk[2], kk[3]}; *(f32x4*)(ks + tok * GS + qr * 8 + 4) = (f32x4){kk[4], kk[5], kk[6], kk[7]};
;         if (NEEDQ) { *(f32x4*)(qs + tok * GS + qr * 8) = (f32x4){qq[0], qq[1], qq[2], qq[3]}; *(f32x4*)(qs + tok * GS + qr * 8 + 4) = (f32x4){qq[4], qq[5], qq[6], qq[7]}; }
.Lg3og_skip1:
	v_lshlrev_b32_e32 v72, 16, v62
	v_and_b32_e32 v73, 0xffff0000, v62
	v_pk_mul_f32 v[74:75], v[72:73], s[16:17] op_sel_hi:[1,0]
	v_lshlrev_b32_e32 v72, 16, v63
	v_and_b32_e32 v73, 0xffff0000, v63
	v_pk_mul_f32 v[76:77], v[72:73], s[16:17] op_sel_hi:[1,0]
	v_lshlrev_b32_e32 v72, 16, v64
	v_and_b32_e32 v73, 0xffff0000, v64
	v_pk_mul_f32 v[78:79], v[72:73], s[16:17] op_sel_hi:[1,0]
	v_lshlrev_b32_e32 v72, 16, v65
	v_and_b32_e32 v73, 0xffff0000, v65
	v_lshlrev_b32_e32 v66, 16, v58
	v_and_b32_e32 v67, 0xffff0000, v58
	v_lshlrev_b32_e32 v68, 16, v59
	v_and_b32_e32 v69, 0xffff0000, v59
	v_lshlrev_b32_e32 v70, 16, v60
	v_and_b32_e32 v71, 0xffff0000, v60
	v_and_b32_e32 v152, 0xffff0000, v61
	v_lshlrev_b32_e32 v153, 16, v61
	s_andn2_b64 vcc, exec, s[68:69]
	v_pk_mul_f32 v[80:81], v[72:73], s[16:17] op_sel_hi:[1,0]
	s_cbranch_vccnz .LBB0_819
	v_pk_mul_f32 v[72:73], v[6:7], v[68:69] op_sel:[1,0]
	v_pk_mul_f32 v[154:155], v[6:7], v[66:67] op_sel_hi:[0,1]
	v_pk_fma_f32 v[176:177], v[2:3], v[68:69], v[72:73] op_sel:[1,0,1] op_sel_hi:[1,1,0] neg_lo:[0,0,1] neg_hi:[0,0,1]
	v_pk_fma_f32 v[68:69], v[2:3], v[68:69], v[72:73] op_sel:[1,0,1] op_sel_hi:[1,1,0]
	v_pk_mul_f32 v[72:73], v[6:7], v[76:77] op_sel:[1,0]
	v_pk_mul_f32 v[156:157], v[2:3], v[66:67]
	v_pk_fma_f32 v[66:67], v[2:3], v[66:67], v[154:155] op_sel:[0,0,1] op_sel_hi:[0,1,0]
	v_pk_fma_f32 v[178:179], v[2:3], v[76:77], v[72:73] op_sel:[1,0,1] op_sel_hi:[1,1,0] neg_lo:[0,0,1] neg_hi:[0,0,1]
	v_pk_fma_f32 v[76:77], v[2:3], v[76:77], v[72:73] op_sel:[1,0,1] op_sel_hi:[1,1,0]
	v_pk_mul_f32 v[72:73], v[8:9], v[70:71] op_sel_hi:[0,1]
	v_pk_fma_f32 v[216:217], v[4:5], v[70:71], v[72:73] op_sel:[0,0,1] op_sel_hi:[0,1,0] neg_lo:[0,0,1] neg_hi:[0,0,1]
	v_pk_fma_f32 v[70:71], v[4:5], v[70:71], v[72:73] op_sel:[0,0,1] op_sel_hi:[0,1,0]
	v_pk_mul_f32 v[72:73], v[8:9], v[78:79] op_sel_hi:[0,1]
	v_mov_b32_e32 v220, v9
	v_mov_b32_e32 v221, v5
	v_mul_f32_e32 v66, v5, v153
	v_pk_fma_f32 v[218:219], v[4:5], v[78:79], v[72:73] op_sel:[0,0,1] op_sel_hi:[0,1,0] neg_lo:[0,0,1] neg_hi:[0,0,1]
	v_pk_fma_f32 v[78:79], v[4:5], v[78:79], v[72:73] op_sel:[0,0,1] op_sel_hi:[0,1,0]
	v_pk_fma_f32 v[72:73], v[220:221], v[152:153], v[66:67] op_sel_hi:[1,1,0] neg_lo:[1,0,0] neg_hi:[1,0,0]
	v_mov_b32_e32 v222, v5
	v_mov_b32_e32 v223, v9
	v_mul_f32_e32 v66, v9, v153
	v_pk_fma_f32 v[152:153], v[222:223], v[152:153], v[66:67] op_sel_hi:[1,1,0]
	v_mul_f32_e32 v66, v9, v81
	v_pk_mul_f32 v[158:159], v[6:7], v[74:75] op_sel_hi:[0,1]
	v_pk_fma_f32 v[222:223], v[222:223], v[80:81], v[66:67] op_sel_hi:[1,1,0] neg_lo:[0,0,1] neg_hi:[0,0,1]
	v_mul_f32_e32 v66, v5, v81
	v_pk_mul_f32 v[160:161], v[2:3], v[74:75]
	v_pk_fma_f32 v[74:75], v[2:3], v[74:75], v[158:159] op_sel:[0,0,1] op_sel_hi:[0,1,0]
	v_pk_fma_f32 v[220:221], v[220:221], v[80:81], v[66:67] op_sel_hi:[1,1,0]
	v_sub_f32_e32 v66, v156, v155
	v_sub_f32_e32 v74, v160, v159
	v_mov_b32_e32 v68, v176
	v_mov_b32_e32 v70, v216
	v_mov_b32_e32 v73, v152
	v_mov_b32_e32 v76, v178
	v_mov_b32_e32 v78, v218
	v_mov_b32_e32 v80, v222
	v_mov_b32_e32 v81, v220
	s_branch .LBB0_820

; __device__ __forceinline__ float bflo(unsigned w) { return __uint_as_float(w << 16); }
; __device__ __forceinline__ float bfhi(unsigned w) { return __uint_as_float(w & 0xffff0000u); }
; #define LDS_WAIT() asm volatile("s_waitcnt lgkmcnt(0)" ::: "memory")
; template <bool NEEDQ>
; __device__ __forceinline__ void gla_stage16(const GlaRaw& R, float* qs, float* ks, float* Bs, float* Be, int tpos0, int dir, const float (&wg)[16], float bgk, int lane) {
;     ...
;         *(f32x4*)(ks + tok * GS + qr * 8) = (f32x4){kk[0], kk[1], kk[2], kk[3]}; *(f32x4*)(ks + tok * GS + qr * 8 + 4) = (f32x4){kk[4], kk[5], kk[6], kk[7]};
;         if (NEEDQ) { *(f32x4*)(qs + tok * GS + qr * 8) = (f32x4){qq[0], qq[1], qq[2], qq[3]}; *(f32x4*)(qs + tok * GS + qr * 8 + 4) = (f32x4){qq[4], qq[5], qq[6], qq[7]}; }
;     }
;     bf16_t* Gs = (bf16_t*)(Be + 64);
;     *(u32x2*)(Gs + lane * 4) = R.graw;
;     LDS_WAIT();
;     {
;         const int k = lane & 31, hf = lane >> 5;
;         float g[8];
; #pragma unroll
;         for (int i = 0; i < 8; ++i) {
;             const u32x4 ga = *(const u32x4*)(Gs + (hf * 8 + i) * 16), gb = *(const u32x4*)(Gs + (hf * 8 + i) * 16 + 8);
;             float x = bgk;
; #pragma unroll
;             for (int j = 0; j < 4; ++j) { x += bflo(ga[j]) * wg[2 * j] + bfhi(ga[j]) * wg[2 * j + 1]; }
; #pragma unroll
;             for (int j = 0; j < 4; ++j) { x += bflo(gb[j]) * wg[8 + 2 * j] + bfhi(gb[j]) * wg[8 + 2 * j + 1]; }
;             g[i] = (fminf(x, 0.f) - __logf(1.f + __expf(-fabsf(x)))) * (0.0625f * LOG2E);
.LBB0_820:
	ds_write_b128 v181, v[66:69] offset:2304
	ds_write_b128 v181, v[70:73] offset:2320
	ds_write_b128 v181, v[74:77]
	ds_write_b128 v181, v[78:81] offset:16
	s_cmp_lg_u64 s[26:27], 0
	s_cbranch_scc1 .Lg3og_w2d1
	s_waitcnt vmcnt(4)
	s_branch .Lg3og_w2done
.Lg3og_w2d1:
	s_waitcnt vmcnt(12)
.Lg3og_w2done:
	ds_write_b64 v212, v[140:141] offset:7168
	s_waitcnt lgkmcnt(0)
	ds_read_b128 v[66:69], v183 offset:7168
	ds_read_b128 v[70:73], v183 offset:7184
	s_waitcnt lgkmcnt(1)
	v_lshlrev_b32_e32 v75, 16, v67
	v_lshlrev_b32_e32 v74, 16, v66
	v_and_b32_e32 v67, 0xffff0000, v67
	v_and_b32_e32 v66, 0xffff0000, v66
	v_pk_mul_f32 v[66:67], v[124:125], v[66:67]
	s_nop 0
	v_pk_fma_f32 v[66:67], v[122:123], v[74:75], v[66:67]
	s_nop 0
	v_add_f32_e32 v66, v97, v66
	v_add_f32_e32 v74, v67, v66
	v_lshlrev_b32_e32 v67, 16, v69
	v_lshlrev_b32_e32 v66, 16, v68
	v_and_b32_e32 v69, 0xffff0000, v69
	v_and_b32_e32 v68, 0xffff0000, v68
	v_pk_mul_f32 v[68:69], v[128:129], v[68:69]
	s_nop 0
	v_pk_fma_f32 v[66:67], v[126:127], v[66:67], v[68:69]
	s_waitcnt lgkmcnt(0)
	v_and_b32_e32 v69, 0xffff0000, v71
	v_add_f32_e32 v66, v66, v74
	v_and_b32_e32 v68, 0xffff0000, v70
	v_add_f32_e32 v74, v67, v66
	v_lshlrev_b32_e32 v67, 16, v71
	v_lshlrev_b32_e32 v66, 16, v70
	v_pk_mul_f32 v[68:69], v[132:133], v[68:69]
	s_nop 0
	v_pk_fma_f32 v[66:67], v[130:131], v[66:67], v[68:69]
	v_and_b32_e32 v69, 0xffff0000, v73
	v_add_f32_e32 v66, v66, v74
	v_and_b32_e32 v68, 0xffff0000, v72
	v_add_f32_e32 v70, v67, v66
	v_lshlrev_b32_e32 v67, 16, v73
	v_lshlrev_b32_e32 v66, 16, v72
	v_pk_mul_f32 v[68:69], v[136:137], v[68:69]
	s_nop 0
	v_pk_fma_f32 v[66:67], v[134:135], v[66:67], v[68:69]
	s_nop 0
	v_add_f32_e32 v66, v66, v70
	v_add_f32_e32 v74, v67, v66
	v_mul_f32_e64 v66, |v74|, s89
	v_exp_f32_e32 v66, v66
	v_min_f32_e32 v74, 0, v74
	v_add_f32_e32 v66, 1.0, v66
	v_cmp_gt_f32_e32 vcc, s82, v66
	s_nop 1
	v_cndmask_b32_e64 v67, 0, 32, vcc
	v_ldexp_f32 v66, v66, v67
	v_log_f32_e32 v75, v66
	ds_read_b128 v[66:69], v183 offset:7200
	ds_read_b128 v[70:73], v183 offset:7216
	v_mul_f32_e32 v76, 0x3f317217, v75
	v_fma_f32 v78, v75, s90, -v76
	s_waitcnt lgkmcnt(1)
	v_lshlrev_b32_e32 v77, 16, v67
	v_lshlrev_b32_e32 v76, 16, v66
	v_and_b32_e32 v67, 0xffff0000, v67
	v_and_b32_e32 v66, 0xffff0000, v66
	v_pk_mul_f32 v[66:67], v[124:125], v[66:67]
	v_fmac_f32_e32 v78, 0x3377d1cf, v75
	v_pk_fma_f32 v[66:67], v[122:123], v[76:77], v[66:67]
	v_fmac_f32_e32 v78, 0x3f317217, v75
	v_add_f32_e32 v66, v97, v66
	v_add_f32_e32 v76, v67, v66
	v_lshlrev_b32_e32 v67, 16, v69
	v_lshlrev_b32_e32 v66, 16, v68
	v_and_b32_e32 v69, 0xffff0000, v69
	v_and_b32_e32 v68, 0xffff0000, v68
	v_pk_mul_f32 v[68:69], v[128:129], v[68:69]
	v_cmp_lt_f32_e64 s[66:67], |v75|, s91
	v_pk_fma_f32 v[66:67], v[126:127], v[66:67], v[68:69]
	s_waitcnt lgkmcnt(0)
	v_and_b32_e32 v69, 0xffff0000, v71
	v_add_f32_e32 v66, v66, v76
	v_and_b32_e32 v68, 0xffff0000, v70
	v_add_f32_e32 v76, v67, v66
	v_lshlrev_b32_e32 v67, 16, v71
	v_lshlrev_b32_e32 v66, 16, v70
	v_pk_mul_f32 v[68:69], v[132:133], v[68:69]
	s_nop 0
	v_pk_fma_f32 v[66:67], v[130:131], v[66:67], v[68:69]
	v_and_b32_e32 v69, 0xffff0000, v73
	v_add_f32_e32 v66, v66, v76
	v_and_b32_e32 v68, 0xffff0000, v72
	v_add_f32_e32 v70, v67, v66
	v_lshlrev_b32_e32 v67, 16, v73
	v_lshlrev_b32_e32 v66, 16, v72
	v_pk_mul_f32 v[68:69], v[136:137], v[68:69]
	s_nop 0
	v_pk_fma_f32 v[66:67], v[134:135], v[66:67], v[68:69]
	v_cndmask_b32_e64 v68, v75, v78, s[66:67]
	v_add_f32_e32 v66, v66, v70
	v_add_f32_e32 v66, v67, v66
	v_mul_f32_e64 v67, |v66|, s89
	v_exp_f32_e32 v67, v67
	v_min_f32_e32 v75, 0, v66
	v_add_f32_e32 v67, 1.0, v67
	v_cmp_gt_f32_e64 s[66:67], s82, v67
	s_nop 1
	v_cndmask_b32_e64 v69, 0, 32, s[66:67]
	v_ldexp_f32 v67, v67, v69
	v_log_f32_e32 v70, v67
	v_cndmask_b32_e32 v67, 0, v230, vcc
	v_sub_f32_e32 v76, v68, v67
	v_mul_f32_e32 v66, 0x3f317217, v70
	v_fma_f32 v71, v70, s90, -v66
	ds_read_b128 v[66:69], v183 offset:7232
	v_fmac_f32_e32 v71, 0x3377d1cf, v70
	v_fmac_f32_e32 v71, 0x3f317217, v70
	v_cmp_lt_f32_e64 vcc, |v70|, s91
	s_nop 1
	v_cndmask_b32_e32 v77, v70, v71, vcc
	ds_read_b128 v[70:73], v183 offset:7248
	s_waitcnt lgkmcnt(1)
	v_lshlrev_b32_e32 v79, 16, v67
	v_lshlrev_b32_e32 v78, 16, v66
	v_and_b32_e32 v67, 0xffff0000, v67
	v_and_b32_e32 v66, 0xffff0000, v66
	v_pk_mul_f32 v[66:67], v[124:125], v[66:67]
	s_nop 0
	v_pk_fma_f32 v[66:67], v[122:123], v[78:79], v[66:67]
	s_nop 0
	v_add_f32_e32 v66, v97, v66
	v_add_f32_e32 v78, v67, v66
	v_lshlrev_b32_e32 v67, 16, v69
	v_lshlrev_b32_e32 v66, 16, v68
	v_and_b32_e32 v69, 0xffff0000, v69
	v_and_b32_e32 v68, 0xffff0000, v68
	v_pk_mul_f32 v[68:69], v[128:129], v[68:69]
	s_nop 0
	v_pk_fma_f32 v[66:67], v[126:127], v[66:67], v[68:69]
	s_waitcnt lgkmcnt(0)
	v_and_b32_e32 v69, 0xffff0000, v71
	v_add_f32_e32 v66, v66, v78
	v_and_b32_e32 v68, 0xffff0000, v70
	v_add_f32_e32 v78, v67, v66
	v_lshlrev_b32_e32 v67, 16, v71
	v_lshlrev_b32_e32 v66, 16, v70
	v_pk_mul_f32 v[68:69], v[132:133], v[68:69]
	s_nop 0
	v_pk_fma_f32 v[66:67], v[130:131], v[66:67], v[68:69]
	v_and_b32_e32 v69, 0xffff0000, v73
	v_add_f32_e32 v66, v66, v78
	v_and_b32_e32 v68, 0xffff0000, v72
	v_add_f32_e32 v70, v67, v66
	v_lshlrev_b32_e32 v67, 16, v73
	v_lshlrev_b32_e32 v66, 16, v72
	v_pk_mul_f32 v[68:69], v[136:137], v[68:69]
	s_nop 0
	v_pk_fma_f32 v[66:67], v[134:135], v[66:67], v[68:69]
	s_nop 0
	v_add_f32_e32 v66, v66, v70
	v_add_f32_e32 v68, v67, v66
	v_mul_f32_e64 v66, |v68|, s89
	v_exp_f32_e32 v69, v66
	v_cndmask_b32_e64 v66, 0, v230, s[66:67]
	v_sub_f32_e32 v77, v77, v66
	v_pk_add_f32 v[66:67], v[74:75], v[76:77] neg_lo:[0,1] neg_hi:[0,1]
	v_add_f32_e32 v69, 1.0, v69
	v_cmp_gt_f32_e32 vcc, s82, v69
	v_min_f32_e32 v76, 0, v68
	v_pk_mul_f32 v[66:67], v[66:67], s[30:31] op_sel_hi:[1,0]
	v_cndmask_b32_e64 v70, 0, 32, vcc
	v_ldexp_f32 v69, v69, v70
	v_log_f32_e32 v77, v69
	ds_read_b128 v[68:71], v183 offset:7264
	v_mul_f32_e32 v72, 0x3f317217, v77
	v_fma_f32 v80, v77, s90, -v72
	ds_read_b128 v[72:75], v183 offset:7280
	s_waitcnt lgkmcnt(1)
; __device__ __forceinline__ float bflo(unsigned w) { return __uint_as_float(w << 16); }
; __device__ __forceinline__ float bfhi(unsigned w) { return __uint_as_float(w & 0xffff0000u); }
; template <bool NEEDQ>
; __device__ __forceinline__ void gla_stage16(const GlaRaw& R, float* qs, float* ks, float* Bs, float* Be, int tpos0, int dir, const float (&wg)[16], float bgk, int lane) {
;     ...
;         for (int i = 0; i < 8; ++i) {
;             const u32x4 ga = *(const u32x4*)(Gs + (hf * 8 + i) * 16), gb = *(const u32x4*)(Gs + (hf * 8 + i) * 16 + 8);
;             float x = bgk;
; #pragma unroll
;             for (int j = 0; j < 4; ++j) { x += bflo(ga[j]) * wg[2 * j] + bfhi(ga[j]) * wg[2 * j + 1]; }
; #pragma unroll
;             for (int j = 0; j < 4; ++j) { x += bflo(gb[j]) * wg[8 + 2 * j] + bfhi(gb[j]) * wg[8 + 2 * j + 1]; }
;             g[i] = (fminf(x, 0.f) - __logf(1.f + __expf(-fabsf(x)))) * (0.0625f * LOG2E);
	v_lshlrev_b32_e32 v79, 16, v69
	v_lshlrev_b32_e32 v78, 16, v68
	v_and_b32_e32 v69, 0xffff0000, v69
	v_and_b32_e32 v68, 0xffff0000, v68
	v_pk_mul_f32 v[68:69], v[124:125], v[68:69]
	v_fmac_f32_e32 v80, 0x3377d1cf, v77
	v_pk_fma_f32 v[68:69], v[122:123], v[78:79], v[68:69]
	v_fmac_f32_e32 v80, 0x3f317217, v77
	v_add_f32_e32 v68, v97, v68
	v_add_f32_e32 v78, v69, v68
	v_lshlrev_b32_e32 v69, 16, v71
	v_lshlrev_b32_e32 v68, 16, v70
	v_and_b32_e32 v71, 0xffff0000, v71
	v_and_b32_e32 v70, 0xffff0000, v70
	v_pk_mul_f32 v[70:71], v[128:129], v[70:71]
	v_cmp_lt_f32_e64 s[66:67], |v77|, s91
	v_pk_fma_f32 v[68:69], v[126:127], v[68:69], v[70:71]
	s_waitcnt lgkmcnt(0)
	v_and_b32_e32 v71, 0xffff0000, v73
	v_add_f32_e32 v68, v68, v78
	v_and_b32_e32 v70, 0xffff0000, v72
	v_add_f32_e32 v78, v69, v68
	v_lshlrev_b32_e32 v69, 16, v73
	v_lshlrev_b32_e32 v68, 16, v72
	v_pk_mul_f32 v[70:71], v[132:133], v[70:71]
	s_nop 0
	v_pk_fma_f32 v[68:69], v[130:131], v[68:69], v[70:71]
	v_and_b32_e32 v71, 0xffff0000, v75
	v_add_f32_e32 v68, v68, v78
	v_and_b32_e32 v70, 0xffff0000, v74
	v_add_f32_e32 v72, v69, v68
	v_lshlrev_b32_e32 v69, 16, v75
	v_lshlrev_b32_e32 v68, 16, v74
	v_pk_mul_f32 v[70:71], v[136:137], v[70:71]
	s_nop 0
	v_pk_fma_f32 v[68:69], v[134:135], v[68:69], v[70:71]
	v_cndmask_b32_e64 v70, v77, v80, s[66:67]
	v_add_f32_e32 v68, v68, v72
	v_add_f32_e32 v68, v69, v68
	v_mul_f32_e64 v69, |v68|, s89
	v_exp_f32_e32 v69, v69
	v_min_f32_e32 v77, 0, v68
	v_add_f32_e32 v69, 1.0, v69
	v_cmp_gt_f32_e64 s[66:67], s82, v69
	s_nop 1
	v_cndmask_b32_e64 v71, 0, 32, s[66:67]
	v_ldexp_f32 v69, v69, v71
	v_log_f32_e32 v72, v69
	v_cndmask_b32_e32 v69, 0, v230, vcc
	v_sub_f32_e32 v78, v70, v69
	v_mul_f32_e32 v68, 0x3f317217, v72
	v_fma_f32 v73, v72, s90, -v68
	ds_read_b128 v[68:71], v183 offset:7296
	v_fmac_f32_e32 v73, 0x3377d1cf, v72
	v_fmac_f32_e32 v73, 0x3f317217, v72
	v_cmp_lt_f32_e64 vcc, |v72|, s91
	s_nop 1
	v_cndmask_b32_e32 v79, v72, v73, vcc
	ds_read_b128 v[72:75], v183 offset:7312
	s_waitcnt lgkmcnt(1)
	v_lshlrev_b32_e32 v81, 16, v69
	v_lshlrev_b32_e32 v80, 16, v68
	v_and_b32_e32 v69, 0xffff0000, v69
	v_and_b32_e32 v68, 0xffff0000, v68
	v_pk_mul_f32 v[68:69], v[124:125], v[68:69]
	s_nop 0
	v_pk_fma_f32 v[68:69], v[122:123], v[80:81], v[68:69]
	s_nop 0
	v_add_f32_e32 v68, v97, v68
	v_add_f32_e32 v80, v69, v68
	v_lshlrev_b32_e32 v69, 16, v71
	v_lshlrev_b32_e32 v68, 16, v70
	v_and_b32_e32 v71, 0xffff0000, v71
	v_and_b32_e32 v70, 0xffff0000, v70
	v_pk_mul_f32 v[70:71], v[128:129], v[70:71]
	s_nop 0
	v_pk_fma_f32 v[68:69], v[126:127], v[68:69], v[70:71]
	s_waitcnt lgkmcnt(0)
	v_and_b32_e32 v71, 0xffff0000, v73
	v_add_f32_e32 v68, v68, v80
	v_and_b32_e32 v70, 0xffff0000, v72
	v_add_f32_e32 v80, v69, v68
	v_lshlrev_b32_e32 v69, 16, v73
	v_lshlrev_b32_e32 v68, 16, v72
	v_pk_mul_f32 v[70:71], v[132:133], v[70:71]
	s_nop 0
	v_pk_fma_f32 v[68:69], v[130:131], v[68:69], v[70:71]
	v_and_b32_e32 v71, 0xffff0000, v75
	v_add_f32_e32 v68, v68, v80
	v_and_b32_e32 v70, 0xffff0000, v74
	v_add_f32_e32 v72, v69, v68
	v_lshlrev_b32_e32 v69, 16, v75
	v_lshlrev_b32_e32 v68, 16, v74
	v_pk_mul_f32 v[70:71], v[136:137], v[70:71]
	s_nop 0
	v_pk_fma_f32 v[68:69], v[134:135], v[68:69], v[70:71]
	s_nop 0
	v_add_f32_e32 v68, v68, v72
	v_add_f32_e32 v70, v69, v68
	v_mul_f32_e64 v68, |v70|, s89
	v_exp_f32_e32 v71, v68
	v_cndmask_b32_e64 v68, 0, v230, s[66:67]
	v_sub_f32_e32 v79, v79, v68
	v_pk_add_f32 v[68:69], v[76:77], v[78:79] neg_lo:[0,1] neg_hi:[0,1]
	v_add_f32_e32 v71, 1.0, v71
	v_cmp_gt_f32_e32 vcc, s82, v71
	v_min_f32_e32 v78, 0, v70
	v_pk_mul_f32 v[68:69], v[68:69], s[30:31] op_sel_hi:[1,0]
	v_cndmask_b32_e64 v72, 0, 32, vcc
	v_ldexp_f32 v71, v71, v72
	v_log_f32_e32 v79, v71
	ds_read_b128 v[70:73], v183 offset:7328
	v_mul_f32_e32 v74, 0x3f317217, v79
	v_fma_f32 v139, v79, s90, -v74
	ds_read_b128 v[74:77], v183 offset:7344
	s_waitcnt lgkmcnt(1)
	v_lshlrev_b32_e32 v81, 16, v71
	v_lshlrev_b32_e32 v80, 16, v70
	v_and_b32_e32 v71, 0xffff0000, v71
	v_and_b32_e32 v70, 0xffff0000, v70
	v_pk_mul_f32 v[70:71], v[124:125], v[70:71]
	v_fmac_f32_e32 v139, 0x3377d1cf, v79
	v_pk_fma_f32 v[70:71], v[122:123], v[80:81], v[70:71]
	v_fmac_f32_e32 v139, 0x3f317217, v79
	v_add_f32_e32 v70, v97, v70
	v_add_f32_e32 v80, v71, v70
	v_lshlrev_b32_e32 v71, 16, v73
	v_lshlrev_b32_e32 v70, 16, v72
	v_and_b32_e32 v73, 0xffff0000, v73
	v_and_b32_e32 v72, 0xffff0000, v72
	v_pk_mul_f32 v[72:73], v[128:129], v[72:73]
	v_cmp_lt_f32_e64 s[66:67], |v79|, s91
	v_pk_fma_f32 v[70:71], v[126:127], v[70:71], v[72:73]
	s_waitcnt lgkmcnt(0)
	v_and_b32_e32 v73, 0xffff0000, v75
	v_add_f32_e32 v70, v70, v80
	v_and_b32_e32 v72, 0xffff0000, v74
	v_add_f32_e32 v80, v71, v70
	v_lshlrev_b32_e32 v71, 16, v75
	v_lshlrev_b32_e32 v70, 16, v74
	v_pk_mul_f32 v[72:73], v[132:133], v[72:73]
	s_nop 0
	v_pk_fma_f32 v[70:71], v[130:131], v[70:71], v[72:73]
	v_and_b32_e32 v73, 0xffff0000, v77
	v_add_f32_e32 v70, v70, v80
	v_and_b32_e32 v72, 0xffff0000, v76
	v_add_f32_e32 v74, v71, v70
	v_lshlrev_b32_e32 v71, 16, v77
	v_lshlrev_b32_e32 v70, 16, v76
	v_pk_mul_f32 v[72:73], v[136:137], v[72:73]
	s_nop 0
	v_pk_fma_f32 v[70:71], v[134:135], v[70:71], v[72:73]
	v_cndmask_b32_e64 v72, v79, v139, s[66:67]
	v_add_f32_e32 v70, v70, v74
	v_add_f32_e32 v70, v71, v70
	v_mul_f32_e64 v71, |v70|, s89
	v_exp_f32_e32 v71, v71
	v_min_f32_e32 v79, 0, v70
	v_add_f32_e32 v71, 1.0, v71
	v_cmp_gt_f32_e64 s[66:67], s82, v71
	s_nop 1
	v_cndmask_b32_e64 v73, 0, 32, s[66:67]
	v_ldexp_f32 v71, v71, v73
	v_log_f32_e32 v74, v71
	v_cndmask_b32_e32 v71, 0, v230, vcc
	v_sub_f32_e32 v80, v72, v71
	v_mul_f32_e32 v70, 0x3f317217, v74
	v_fma_f32 v75, v74, s90, -v70
	ds_read_b128 v[70:73], v183 offset:7360
	v_fmac_f32_e32 v75, 0x3377d1cf, v74
	v_fmac_f32_e32 v75, 0x3f317217, v74
	v_cmp_lt_f32_e64 vcc, |v74|, s91
	s_nop 1
	v_cndmask_b32_e32 v81, v74, v75, vcc
	ds_read_b128 v[74:77], v183 offset:7376
	s_waitcnt lgkmcnt(1)
; __device__ __forceinline__ float bflo(unsigned w) { return __uint_as_float(w << 16); }
; __device__ __forceinline__ float bfhi(unsigned w) { return __uint_as_float(w & 0xffff0000u); }
; template <bool NEEDQ>
; __device__ __forceinline__ void gla_stage16(const GlaRaw& R, float* qs, float* ks, float* Bs, float* Be, int tpos0, int dir, const float (&wg)[16], float bgk, int lane) {
;     ...
;         for (int i = 0; i < 8; ++i) {
;             const u32x4 ga = *(const u32x4*)(Gs + (hf * 8 + i) * 16), gb = *(const u32x4*)(Gs + (hf * 8 + i) * 16 + 8);
;             float x = bgk;
; #pragma unroll
;             for (int j = 0; j < 4; ++j) { x += bflo(ga[j]) * wg[2 * j] + bfhi(ga[j]) * wg[2 * j + 1]; }
; #pragma unroll
;             for (int j = 0; j < 4; ++j) { x += bflo(gb[j]) * wg[8 + 2 * j] + bfhi(gb[j]) * wg[8 + 2 * j + 1]; }
;             g[i] = (fminf(x, 0.f) - __logf(1.f + __expf(-fabsf(x)))) * (0.0625f * LOG2E);
;         }
;         if (dir == 0) {
; #pragma unroll
;             for (int i = 1; i < 8; ++i) g[i] += g[i - 1];
;             const float other = __shfl_xor(g[7], 32);
;             if (hf == 1) {
; #pragma unroll
;                 for (int i = 0; i < 8; ++i) g[i] += other;
;                 Be[k] = g[7]; }
;         } else {
; #pragma unroll
;             for (int i = 6; i >= 0; --i) g[i] += g[i + 1];
;             const float other = __shfl_xor(g[0], 32);
;             if (hf == 0) {
; #pragma unroll
;                 for (int i = 0; i < 8; ++i) g[i] += other;
;                 Be[k] = g[0]; }
;         }
	v_lshlrev_b32_e32 v153, 16, v71
	v_lshlrev_b32_e32 v152, 16, v70
	v_and_b32_e32 v71, 0xffff0000, v71
	v_and_b32_e32 v70, 0xffff0000, v70
	v_pk_mul_f32 v[70:71], v[124:125], v[70:71]
	s_nop 0
	v_pk_fma_f32 v[70:71], v[122:123], v[152:153], v[70:71]
	s_nop 0
	v_add_f32_e32 v70, v97, v70
	v_add_f32_e32 v139, v71, v70
	v_lshlrev_b32_e32 v71, 16, v73
	v_lshlrev_b32_e32 v70, 16, v72
	v_and_b32_e32 v73, 0xffff0000, v73
	v_and_b32_e32 v72, 0xffff0000, v72
	v_pk_mul_f32 v[72:73], v[128:129], v[72:73]
	s_nop 0
	v_pk_fma_f32 v[70:71], v[126:127], v[70:71], v[72:73]
	s_waitcnt lgkmcnt(0)
	v_and_b32_e32 v73, 0xffff0000, v75
	v_add_f32_e32 v70, v70, v139
	v_and_b32_e32 v72, 0xffff0000, v74
	v_add_f32_e32 v139, v71, v70
	v_lshlrev_b32_e32 v71, 16, v75
	v_lshlrev_b32_e32 v70, 16, v74
	v_pk_mul_f32 v[72:73], v[132:133], v[72:73]
	s_nop 0
	v_pk_fma_f32 v[70:71], v[130:131], v[70:71], v[72:73]
	v_and_b32_e32 v73, 0xffff0000, v77
	v_add_f32_e32 v70, v70, v139
	v_and_b32_e32 v72, 0xffff0000, v76
	v_add_f32_e32 v74, v71, v70
	v_lshlrev_b32_e32 v71, 16, v77
	v_lshlrev_b32_e32 v70, 16, v76
	v_pk_mul_f32 v[72:73], v[136:137], v[72:73]
	s_nop 0
	v_pk_fma_f32 v[70:71], v[134:135], v[70:71], v[72:73]
	s_nop 0
	v_add_f32_e32 v70, v70, v74
	v_add_f32_e32 v74, v71, v70
	v_mul_f32_e64 v70, |v74|, s89
	v_exp_f32_e32 v72, v70
	v_cndmask_b32_e64 v70, 0, v230, s[66:67]
	v_sub_f32_e32 v81, v81, v70
	v_pk_add_f32 v[70:71], v[78:79], v[80:81] neg_lo:[0,1] neg_hi:[0,1]
	v_add_f32_e32 v72, 1.0, v72
	v_cmp_gt_f32_e32 vcc, s82, v72
	ds_read_b128 v[78:81], v183 offset:7408
	s_nop 0
	v_cndmask_b32_e64 v73, 0, 32, vcc
	v_ldexp_f32 v72, v72, v73
	v_log_f32_e32 v139, v72
	v_pk_mul_f32 v[72:73], v[70:71], s[30:31] op_sel_hi:[1,0]
	v_min_f32_e32 v70, 0, v74
	ds_read_b128 v[74:77], v183 offset:7392
	v_mul_f32_e32 v71, 0x3f317217, v139
	v_fma_f32 v71, v139, s90, -v71
	v_fmac_f32_e32 v71, 0x3377d1cf, v139
	v_fmac_f32_e32 v71, 0x3f317217, v139
	s_waitcnt lgkmcnt(0)
	v_lshlrev_b32_e32 v153, 16, v75
	v_lshlrev_b32_e32 v152, 16, v74
	v_and_b32_e32 v75, 0xffff0000, v75
	v_and_b32_e32 v74, 0xffff0000, v74
	v_pk_mul_f32 v[74:75], v[124:125], v[74:75]
	v_cmp_lt_f32_e64 s[66:67], |v139|, s91
	v_pk_fma_f32 v[74:75], v[122:123], v[152:153], v[74:75]
	s_nop 0
	v_add_f32_e32 v74, v97, v74
	v_add_f32_e32 v143, v75, v74
	v_lshlrev_b32_e32 v75, 16, v77
	v_lshlrev_b32_e32 v74, 16, v76
	v_and_b32_e32 v77, 0xffff0000, v77
	v_and_b32_e32 v76, 0xffff0000, v76
	v_pk_mul_f32 v[76:77], v[128:129], v[76:77]
	v_cndmask_b32_e64 v71, v139, v71, s[66:67]
	v_pk_fma_f32 v[74:75], v[126:127], v[74:75], v[76:77]
	v_and_b32_e32 v77, 0xffff0000, v79
	v_add_f32_e32 v74, v74, v143
	v_and_b32_e32 v76, 0xffff0000, v78
	v_add_f32_e32 v143, v75, v74
	v_lshlrev_b32_e32 v75, 16, v79
	v_lshlrev_b32_e32 v74, 16, v78
	v_pk_mul_f32 v[76:77], v[132:133], v[76:77]
	s_nop 0
	v_pk_fma_f32 v[74:75], v[130:131], v[74:75], v[76:77]
	v_and_b32_e32 v77, 0xffff0000, v81
	v_add_f32_e32 v74, v74, v143
	v_and_b32_e32 v76, 0xffff0000, v80
	v_add_f32_e32 v78, v75, v74
	v_lshlrev_b32_e32 v75, 16, v81
	v_lshlrev_b32_e32 v74, 16, v80
	v_pk_mul_f32 v[76:77], v[136:137], v[76:77]
	s_nop 0
	v_pk_fma_f32 v[74:75], v[134:135], v[74:75], v[76:77]
	s_nop 0
	v_add_f32_e32 v74, v74, v78
	v_add_f32_e32 v75, v75, v74
	v_mul_f32_e64 v74, |v75|, s89
	v_exp_f32_e32 v74, v74
	s_nop 0
	v_add_f32_e32 v74, 1.0, v74
	v_cmp_gt_f32_e64 s[66:67], s82, v74
	s_nop 1
	v_cndmask_b32_e64 v76, 0, 32, s[66:67]
	v_ldexp_f32 v74, v74, v76
	v_log_f32_e32 v76, v74
	v_cndmask_b32_e32 v74, 0, v230, vcc
	v_sub_f32_e32 v74, v71, v74
	v_min_f32_e32 v71, 0, v75
	v_mul_f32_e32 v75, 0x3f317217, v76
	v_fma_f32 v75, v76, s90, -v75
	v_fmac_f32_e32 v75, 0x3377d1cf, v76
	v_fmac_f32_e32 v75, 0x3f317217, v76
	v_cmp_lt_f32_e64 vcc, |v76|, s91
	s_nop 1
	v_cndmask_b32_e32 v75, v76, v75, vcc
	v_cndmask_b32_e64 v76, 0, v230, s[66:67]
	v_sub_f32_e32 v75, v75, v76
	v_pk_add_f32 v[70:71], v[70:71], v[74:75] neg_lo:[0,1] neg_hi:[0,1]
	s_nop 0
	v_pk_mul_f32 v[156:157], v[70:71], s[30:31] op_sel_hi:[1,0]
	v_and_b32_e32 v71, 64, v228
	v_xor_b32_e32 v70, 32, v228
	v_add_u32_e32 v143, 64, v71
	v_cmp_lt_i32_e32 vcc, v70, v143
	v_cndmask_b32_e64 v71, 0, 1, s[74:75]
	v_cmp_ne_u32_e64 s[66:67], 1, v71
	v_cndmask_b32_e32 v70, v228, v70, vcc
	s_andn2_b64 vcc, exec, s[74:75]
	v_lshlrev_b32_e32 v178, 2, v70
	s_cbranch_vccnz .LBB0_824
	v_pk_add_f32 v[76:77], v[156:157], v[156:157] op_sel:[0,1] op_sel_hi:[1,0]
	s_mov_b64 vcc, 0
	v_pk_add_f32 v[78:79], v[72:73], v[76:77] op_sel:[1,0] op_sel_hi:[0,1]
	v_pk_add_f32 v[70:71], v[72:73], v[78:79]
	s_mov_b64 s[78:79], 0
	v_pk_add_f32 v[80:81], v[68:69], v[70:71] op_sel:[1,0] op_sel_hi:[0,1]
	v_pk_add_f32 v[74:75], v[68:69], v[80:81]
	v_mov_b32_e32 v152, v157
	v_pk_add_f32 v[154:155], v[66:67], v[74:75] op_sel:[1,0] op_sel_hi:[0,1]
	v_pk_add_f32 v[158:159], v[66:67], v[154:155]
	ds_bpermute_b32 v160, v178, v158
	s_and_saveexec_b64 s[34:35], s[38:39]
	s_cbranch_execz .LBB0_823
	v_mov_b32_e32 v159, v154
	v_mov_b32_e32 v75, v80
	v_mov_b32_e32 v71, v78
	v_mov_b32_e32 v77, v157
	s_waitcnt lgkmcnt(0)
	v_pk_add_f32 v[158:159], v[158:159], v[160:161] op_sel_hi:[1,0]
	v_pk_add_f32 v[74:75], v[74:75], v[160:161] op_sel_hi:[1,0]
	v_pk_add_f32 v[70:71], v[70:71], v[160:161] op_sel_hi:[1,0]
	v_pk_add_f32 v[78:79], v[76:77], v[160:161] op_sel_hi:[1,0]
	s_mov_b64 s[78:79], exec
	v_mov_b32_e32 v77, v158
	v_mov_b32_e32 v152, v79
	v_mov_b32_e32 v76, v78
	v_mov_b32_e32 v78, v71
	v_mov_b32_e32 v80, v75
	v_mov_b32_e32 v154, v159

; __device__ __forceinline__ unsigned pk2(float lo, float hi) { return pg8::cvt_pk_bf16(lo, hi); }
; __device__ __forceinline__ void gla_step3(ParamsK p, int l, unsigned char* smem) {
;     ...
;                 const f32x4 ba = *(const f32x4*)(Bs + fr * GS + fq * 4), bb = *(const f32x4*)(Bs + fr * GS + 16 + fq * 4);
;                 const f32x4 qa = *(const f32x4*)(qs + fr * GS + fq * 4), qb = *(const f32x4*)(qs + fr * GS + 16 + fq * 4);
;                 const f32x4 ka = *(const f32x4*)(ks + fr * GS + fq * 4), kc = *(const f32x4*)(ks + fr * GS + 16 + fq * 4);
;                 u32x4 qw, kw;
;                 qw.x = pk2(qa[0] * EX2(ba[0]), qa[1] * EX2(ba[1])); qw.y = pk2(qa[2] * EX2(ba[2]), qa[3] * EX2(ba[3]));
;                 qw.z = pk2(qb[0] * EX2(bb[0]), qb[1] * EX2(bb[1])); qw.w = pk2(qb[2] * EX2(bb[2]), qb[3] * EX2(bb[3]));
;                 kw.x = pk2(ka[0] * EX2(-ba[0]), ka[1] * EX2(-ba[1])); kw.y = pk2(ka[2] * EX2(-ba[2]), ka[3] * EX2(-ba[3]));
;                 kw.z = pk2(kc[0] * EX2(-bb[0]), kc[1] * EX2(-bb[1])); kw.w = pk2(kc[2] * EX2(-bb[2]), kc[3] * EX2(-bb[3]));
;                 const bf16x8 Qd = as_bf16x8(qw), Kd = as_bf16x8(kw);
;                 bf16x4 ke[2]; f32x4 dec[2]; gla_state_ops(ks, Bs, Be, fr, fq, ke, dec);
;                 f32x4 AT = __builtin_amdgcn_mfma_f32_16x16x32_bf16(Kd, Qd, (f32x4){0.f, 0.f, 0.f, 0.f}, 0, 0, 0);
; #pragma unroll
;                 for (int j = 0; j < 4; ++j) { const int pp = fq * 4 + j; const bool keep = dir == 0 ? (pp <= fr) : (pp >= fr); AT[j] = keep ? AT[j] : 0.f; }
;                 u32x2 aw; aw.x = pk2(AT[0], AT[1]); aw.y = pk2(AT[2], AT[3]);
;                 const bf16x4 atb = as_bf16x4(aw);
;                 f32x4 O[4];
; #pragma unroll
;                 for (int db = 0; db < 4; ++db) {
;                     const f32x4 Oa = __builtin_amdgcn_mfma_f32_16x16x16bf16_1k(vt[db], atb, (f32x4){0.f, 0.f, 0.f, 0.f}, 0, 0, 0);
;                     u32x4 sw; sw.x = pk2(S[0][db][0], S[0][db][1]); sw.y = pk2(S[0][db][2], S[0][db][3]); sw.z = pk2(S[1][db][0], S[1][db][1]); sw.w = pk2(S[1][db][2], S[1][db][3]);
;                     const f32x4 Ob = __builtin_amdgcn_mfma_f32_16x16x32_bf16(as_bf16x8(sw), Qd, (f32x4){0.f, 0.f, 0.f, 0.f}, 0, 0, 0);
;                     O[db] = Oa + Ob;
;                 }
; #pragma unroll
;                 for (int kb = 0; kb < 2; ++kb)
; #pragma unroll
.LBB0_834:
	ds_read_b128 v[70:73], v186 offset:4608
	ds_read_b128 v[74:77], v186 offset:4672
	s_waitcnt lgkmcnt(7)
	ds_read_b128 v[66:69], v186
	ds_read_b128 v[78:81], v186 offset:64
	ds_read_b128 v[152:155], v186 offset:2304
	ds_read_b128 v[156:159], v186 offset:2368
	s_waitcnt lgkmcnt(5)
	v_exp_f32_e32 v160, v70
	v_exp_f32_e32 v161, v71
	v_exp_f32_e32 v176, v72
	v_exp_f32_e32 v177, v73
	v_exp_f32_e64 v70, -v70
	v_exp_f32_e64 v71, -v71
	v_exp_f32_e64 v72, -v72
	v_exp_f32_e64 v73, -v73
	s_waitcnt lgkmcnt(3)
	v_pk_mul_f32 v[66:67], v[160:161], v[66:67]
	s_waitcnt lgkmcnt(1)
	v_pk_mul_f32 v[70:71], v[70:71], v[152:153]
	v_exp_f32_e32 v160, v74
	v_pk_mul_f32 v[72:73], v[72:73], v[154:155]
	v_exp_f32_e32 v161, v75
	v_cvt_pk_bf16_f32 v70, v70, v71
	v_cvt_pk_bf16_f32 v71, v72, v73
	v_exp_f32_e64 v72, -v74
	v_exp_f32_e64 v73, -v75
	v_exp_f32_e64 v74, -v76
	v_exp_f32_e64 v75, -v77
	v_pk_mul_f32 v[68:69], v[176:177], v[68:69]
	v_exp_f32_e32 v176, v76
	v_add_u32_e32 v76, 0x1800, v188
	v_exp_f32_e32 v177, v77
	ds_read2_b32 v[152:153], v76 offset0:192 offset1:208
	ds_read2st64_b32 v[76:77], v189 offset0:9 offset1:18
	s_waitcnt lgkmcnt(2)
	v_pk_mul_f32 v[72:73], v[72:73], v[156:157]
	v_pk_mul_f32 v[74:75], v[74:75], v[158:159]
	v_cvt_pk_bf16_f32 v72, v72, v73
	v_cvt_pk_bf16_f32 v73, v74, v75
	v_add_u32_e32 v75, 0x1000, v190
	ds_read2_b32 v[154:155], v75 offset0:144 offset1:164
	v_cvt_pk_bf16_f32 v66, v66, v67
	v_cvt_pk_bf16_f32 v67, v68, v69
	v_pk_mul_f32 v[68:69], v[160:161], v[78:79]
	v_pk_mul_f32 v[78:79], v[176:177], v[80:81]
	v_cvt_pk_bf16_f32 v68, v68, v69
	v_cvt_pk_bf16_f32 v69, v78, v79
	s_waitcnt lgkmcnt(1)
	v_sub_f32_e32 v74, v152, v77
	v_add_u32_e32 v77, 0x800, v190
	ds_read2_b32 v[78:79], v75 offset0:200 offset1:236
	ds_read2_b32 v[160:161], v77 offset0:80 offset1:100
	s_waitcnt lgkmcnt(2)
	v_sub_f32_e32 v75, v152, v155
	v_exp_f32_e32 v74, v74
	v_exp_f32_e32 v75, v75
	ds_read2_b32 v[80:81], v77 offset0:136 offset1:172
	s_waitcnt lgkmcnt(2)
	v_sub_f32_e32 v77, v152, v78
	v_exp_f32_e32 v78, v77
	v_sub_f32_e32 v77, v152, v79
	v_exp_f32_e32 v79, v77
	s_waitcnt lgkmcnt(1)
	v_mov_b32_e32 v77, v161
	v_pk_mul_f32 v[156:157], v[76:77], v[74:75]
	ds_read_b128 v[74:77], v187 offset:6912
	s_waitcnt lgkmcnt(1)
	v_pk_mul_f32 v[78:79], v[80:81], v[78:79]
	v_mfma_f32_16x16x32_bf16 v[70:73], v[70:73], v[66:69], 0
	v_cvt_pk_bf16_f32 v177, v78, v79
	ds_read_b128 v[78:81], v187 offset:6976
	s_waitcnt lgkmcnt(1)
	v_exp_f32_e32 v242, v74
	v_add_u32_e32 v74, 0x1000, v191
	v_exp_f32_e32 v243, v75
	v_exp_f32_e32 v244, v76
	ds_read2_b32 v[74:75], v74 offset0:164 offset1:200
	v_add_u32_e32 v76, 0x800, v191
	ds_read2_b32 v[216:217], v76 offset0:100 offset1:136
	ds_read_b32 v221, v191 offset:2736
	ds_read_b32 v152, v191 offset:5040
	v_sub_f32_e32 v76, v153, v154
	s_waitcnt lgkmcnt(3)
	v_sub_f32_e32 v139, v153, v75
	v_sub_f32_e32 v74, v153, v74
	v_exp_f32_e32 v222, v139
	s_waitcnt lgkmcnt(0)
	v_sub_f32_e32 v139, v153, v152
	v_exp_f32_e32 v218, v76
	v_exp_f32_e32 v219, v74
	v_exp_f32_e32 v223, v139
	v_mov_b32_e32 v161, v216
	v_mov_b32_e32 v220, v217
	v_cndmask_b32_e64 v70, 0, v70, s[58:59]
	v_cndmask_b32_e64 v71, 0, v71, s[60:61]
	v_cndmask_b32_e64 v72, 0, v72, s[62:63]
	v_cndmask_b32_e64 v73, 0, v73, s[64:65]
	v_pk_mul_f32 v[160:161], v[160:161], v[218:219]
	v_pk_mul_f32 v[224:225], v[220:221], v[222:223]
	v_cvt_pk_bf16_f32 v238, v70, v71
	v_cvt_pk_bf16_f32 v239, v72, v73
	v_cvt_pk_bf16_f32 v70, v26, v27
	v_cvt_pk_bf16_f32 v71, v28, v29
	v_cvt_pk_bf16_f32 v72, v42, v43
	v_cvt_pk_bf16_f32 v73, v44, v45
	v_cvt_pk_bf16_f32 v152, v30, v31
	v_cvt_pk_bf16_f32 v153, v32, v33
	v_cvt_pk_bf16_f32 v154, v46, v47
	v_cvt_pk_bf16_f32 v155, v48, v49
	v_cvt_pk_bf16_f32 v216, v34, v35
	v_cvt_pk_bf16_f32 v217, v36, v37
	v_cvt_pk_bf16_f32 v218, v50, v51
	v_cvt_pk_bf16_f32 v219, v52, v53
	v_cvt_pk_bf16_f32 v160, v160, v161
	v_cvt_pk_bf16_f32 v161, v224, v225
	v_cvt_pk_bf16_f32 v224, v38, v39
	v_cvt_pk_bf16_f32 v225, v40, v41
	v_cvt_pk_bf16_f32 v226, v54, v55
	v_cvt_pk_bf16_f32 v227, v56, v57
	v_cvt_pk_bf16_f32 v176, v156, v157
	v_exp_f32_e32 v245, v77
	v_exp_f32_e32 v246, v78
	v_exp_f32_e32 v247, v79
	v_exp_f32_e32 v248, v80
	v_exp_f32_e32 v249, v81
	v_mfma_f32_16x16x16_bf16 v[74:77], v[150:151], v[238:239], 0
	v_mul_f32_e64 v28, v28, v244
	v_mul_f32_e64 v29, v29, v245
	v_pk_mul_f32 v[26:27], v[26:27], v[242:243]
	v_pk_mul_f32 v[32:33], v[32:33], v[244:245]
	v_mfma_f32_16x16x32_bf16 v[70:73], v[70:73], v[66:69], 0
	v_mul_f32_e64 v30, v30, v242
	v_mul_f32_e64 v31, v31, v243
	v_pk_mul_f32 v[36:37], v[36:37], v[244:245]
	v_pk_mul_f32 v[34:35], v[34:35], v[242:243]
	v_mfma_f32_16x16x16_bf16 v[156:159], v[148:149], v[238:239], 0
	v_mul_f32_e64 v40, v40, v244
	v_mul_f32_e64 v41, v41, v245
	v_pk_mul_f32 v[38:39], v[38:39], v[242:243]
	v_pk_mul_f32 v[44:45], v[44:45], v[248:249]
	v_mfma_f32_16x16x32_bf16 v[152:155], v[152:155], v[66:69], 0
	v_mul_f32_e64 v42, v42, v246
	v_mul_f32_e64 v43, v43, v247
	v_pk_mul_f32 v[48:49], v[48:49], v[248:249]
	v_pk_mul_f32 v[46:47], v[46:47], v[246:247]
	v_mfma_f32_16x16x16_bf16 v[220:223], v[146:147], v[238:239], 0
	v_mul_f32_e64 v52, v52, v248
	v_mul_f32_e64 v53, v53, v249
	v_pk_mul_f32 v[50:51], v[50:51], v[246:247]
	v_pk_mul_f32 v[56:57], v[56:57], v[248:249]
	v_mfma_f32_16x16x32_bf16 v[216:219], v[216:219], v[66:69], 0
	v_mul_f32_e64 v54, v54, v246
	v_mul_f32_e64 v55, v55, v247
	s_and_b64 vcc, exec, s[66:67]
	s_mov_b64 s[34:35], -1
	v_mfma_f32_16x16x16_bf16 v[238:241], v[144:145], v[238:239], 0
	v_mfma_f32_16x16x32_bf16 v[224:227], v[224:227], v[66:69], 0
	v_add_f32_e64 v66, v76, v72
	v_add_f32_e64 v67, v77, v73
	v_pk_add_f32 v[68:69], v[74:75], v[70:71]
	v_pk_add_f32 v[70:71], v[158:159], v[154:155]
	v_mfma_f32_16x16x16_bf16 v[26:29], v[176:177], v[150:151], v[26:29]
	v_add_f32_e64 v72, v156, v152
	v_add_f32_e64 v73, v157, v153
	v_pk_add_f32 v[74:75], v[222:223], v[218:219]
	v_pk_add_f32 v[78:79], v[220:221], v[216:217]
	v_mfma_f32_16x16x16_bf16 v[30:33], v[176:177], v[148:149], v[30:33]
	v_add_f32_e64 v76, v240, v226
	v_add_f32_e64 v77, v241, v227
	v_pk_add_f32 v[80:81], v[238:239], v[224:225]
	v_mfma_f32_16x16x16_bf16 v[34:37], v[176:177], v[146:147], v[34:37]
	v_mfma_f32_16x16x16_bf16 v[38:41], v[176:177], v[144:145], v[38:41]
	v_mfma_f32_16x16x16_bf16 v[42:45], v[160:161], v[150:151], v[42:45]
	v_mfma_f32_16x16x16_bf16 v[46:49], v[160:161], v[148:149], v[46:49]
	v_mfma_f32_16x16x16_bf16 v[50:53], v[160:161], v[146:147], v[50:53]
	v_mfma_f32_16x16x16_bf16 v[54:57], v[160:161], v[144:145], v[54:57]
	s_cbranch_vccnz .LBB0_836
; __device__ __forceinline__ float bflo(unsigned w) { return __uint_as_float(w << 16); }
; __device__ __forceinline__ float bfhi(unsigned w) { return __uint_as_float(w & 0xffff0000u); }
; __device__ __forceinline__ unsigned pk2(float lo, float hi) { return pg8::cvt_pk_bf16(lo, hi); }
; __device__ __forceinline__ float silu_f(float v) { return v * __builtin_amdgcn_rcpf(1.f + __expf(-v)); }
; __device__ __forceinline__ void gla_step3(ParamsK p, int l, unsigned char* smem) {
;     ...
;                     for (int db = 0; db < 4; ++db) { const u32x2 ow = *(const u32x2*)(OG + (size_t)row * 384 + h * 64 + db * 16 + fq * 4); og[db] = (f32x4){bflo(ow.x), bfhi(ow.x), bflo(ow.y), bfhi(ow.y)};
;     ...
;                     float ss = 0.f;
; #pragma unroll
;                     for (int db = 0; db < 4; ++db) { O[db] = O[db] + og[db]; ss += (O[db][0] * O[db][0] + O[db][1] * O[db][1]) + (O[db][2] * O[db][2] + O[db][3] * O[db][3]); }
;                     ss += __shfl_xor(ss, 16); ss += __shfl_xor(ss, 32);
;                     const float rstd = rsqrtf(ss * (1.f / 64.f) + 1e-6f);
; #pragma unroll
;                     for (int db = 0; db < 4; ++db) { const f32x4 n4 = *(const f32x4*)(ngp + db * 16 + fq * 4);
;                         const float r0 = bflo(rgw[db].x), r1 = bfhi(rgw[db].x), r2 = bflo(rgw[db].y), r3 = bfhi(rgw[db].y);
;                         u32x2 w; w.x = pk2(O[db][0] * rstd * n4[0] * silu_f(r0), O[db][1] * rstd * n4[1] * silu_f(r1));
;                         w.y = pk2(O[db][2] * rstd * n4[2] * silu_f(r2), O[db][3] * rstd * n4[3] * silu_f(r3));
;                         *(u32x2*)(MIX + (size_t)row * DM + h * 64 + db * 16 + fq * 4) = w; }
	v_lshlrev_b32_e32 v10, 16, v12
	v_and_b32_e32 v11, 0xffff0000, v12
	v_lshlrev_b32_e32 v12, 16, v13
	v_and_b32_e32 v13, 0xffff0000, v13
	v_lshlrev_b32_e32 v14, 16, v16
	v_and_b32_e32 v15, 0xffff0000, v16
	v_lshlrev_b32_e32 v16, 16, v17
	v_and_b32_e32 v17, 0xffff0000, v17
	v_lshlrev_b32_e32 v18, 16, v20
	v_and_b32_e32 v19, 0xffff0000, v20
	v_lshlrev_b32_e32 v20, 16, v21
	v_and_b32_e32 v21, 0xffff0000, v21
	v_lshlrev_b32_e32 v22, 16, v24
	v_and_b32_e32 v23, 0xffff0000, v24
	v_lshlrev_b32_e32 v24, 16, v25
	v_and_b32_e32 v25, 0xffff0000, v25
	v_pk_add_f32 v[160:161], v[66:67], v[12:13]
	v_pk_add_f32 v[176:177], v[68:69], v[10:11]
	v_pk_mul_f32 v[144:145], v[160:161], v[160:161]
	v_pk_mul_f32 v[146:147], v[176:177], v[176:177]
	v_pk_add_f32 v[156:157], v[70:71], v[16:17]
	v_pk_mov_b32 v[148:149], v[146:147], v[144:145] op_sel:[1,0]
	v_mov_b32_e32 v147, v145
	v_pk_add_f32 v[158:159], v[72:73], v[14:15]
	v_pk_add_f32 v[144:145], v[148:149], v[146:147]
	v_pk_mul_f32 v[146:147], v[156:157], v[156:157]
	v_pk_mul_f32 v[148:149], v[158:159], v[158:159]
	v_pk_add_f32 v[144:145], v[144:145], v[144:145] op_sel:[0,1] op_sel_hi:[1,0]
	v_pk_mov_b32 v[150:151], v[148:149], v[146:147] op_sel:[1,0]
	v_mov_b32_e32 v149, v147
	v_pk_add_f32 v[148:149], v[150:151], v[148:149]
	v_pk_add_f32 v[150:151], v[80:81], v[22:23]
	v_pk_add_f32 v[148:149], v[148:149], v[148:149] op_sel:[0,1] op_sel_hi:[1,0]
	v_mul_f32_e32 v139, v150, v150
	v_mul_f32_e32 v179, v151, v151
	v_pk_add_f32 v[152:153], v[74:75], v[20:21]
	v_pk_add_f32 v[154:155], v[78:79], v[18:19]
	v_mov_b32_e32 v145, v139
	v_mov_b32_e32 v149, v179
	v_pk_add_f32 v[146:147], v[76:77], v[24:25]
	v_pk_add_f32 v[144:145], v[144:145], v[148:149]
	v_mul_f32_e32 v148, v155, v155
	v_mul_f32_e32 v216, v153, v153
	v_mul_f32_e32 v215, v146, v146
	v_mul_f32_e32 v218, v147, v147
	v_pk_fma_f32 v[148:149], v[154:155], v[154:155], v[148:149] op_sel_hi:[1,1,0]
	v_pk_fma_f32 v[216:217], v[152:153], v[152:153], v[216:217] op_sel_hi:[1,1,0]
	v_mov_b32_e32 v149, v215
	v_mov_b32_e32 v217, v218
	v_pk_add_f32 v[148:149], v[148:149], v[216:217]
	ds_read_b128 v[216:219], v237 offset:8192
	v_pk_add_f32 v[144:145], v[144:145], v[148:149]
	v_and_b32_e32 v179, 0xffff0000, v102
	v_add_f32_e32 v139, v144, v145
	v_xor_b32_e32 v144, 16, v228
	v_cmp_lt_i32_e32 vcc, v144, v143
	s_mov_b64 s[34:35], 0
	s_nop 0
	v_cndmask_b32_e32 v143, v228, v144, vcc
	v_lshlrev_b32_e32 v143, 2, v143
	ds_bpermute_b32 v143, v143, v139
	s_waitcnt lgkmcnt(0)
	v_add_f32_e32 v139, v139, v143
	ds_bpermute_b32 v143, v178, v139
	v_lshlrev_b32_e32 v178, 16, v102
	s_waitcnt lgkmcnt(0)
	v_add_f32_e32 v139, v139, v143
	v_fmamk_f32 v139, v139, 0x3c800000, v162
	v_cmp_gt_f32_e32 vcc, s82, v139
	v_mul_f32_e32 v143, 0x4b800000, v139
	s_nop 0
	v_cndmask_b32_e32 v139, v139, v143, vcc
	v_rsq_f32_e32 v139, v139
	s_nop 0
	v_mul_f32_e32 v143, 0x45800000, v139
	v_cndmask_b32_e32 v148, v139, v143, vcc
	v_mul_f32_e32 v139, 0xbfb8aa3b, v178
	v_exp_f32_e32 v139, v139
	v_pk_mul_f32 v[176:177], v[176:177], v[148:149] op_sel_hi:[1,0]
	v_pk_mul_f32 v[160:161], v[160:161], v[148:149] op_sel_hi:[1,0]
	v_ashrrev_i32_e32 v143, 31, v142
	v_add_f32_e32 v139, 1.0, v139
	v_rcp_f32_e32 v220, v139
	v_mul_f32_e32 v139, 0xbfb8aa3b, v179
	v_exp_f32_e32 v139, v139
	v_lshlrev_b64 v[144:145], 11, v[142:143]
	v_lshl_add_u64 v[144:145], v[110:111], 0, v[144:145]
	v_pk_mul_f32 v[158:159], v[158:159], v[148:149] op_sel_hi:[1,0]
	v_add_f32_e32 v139, 1.0, v139
	v_rcp_f32_e32 v221, v139
	v_pk_mul_f32 v[156:157], v[156:157], v[148:149] op_sel_hi:[1,0]
	v_pk_mul_f32 v[154:155], v[154:155], v[148:149] op_sel_hi:[1,0]
	v_pk_mul_f32 v[152:153], v[152:153], v[148:149] op_sel_hi:[1,0]
	v_pk_mul_f32 v[178:179], v[220:221], v[178:179]
	v_pk_mul_f32 v[150:151], v[150:151], v[148:149] op_sel_hi:[1,0]
	s_waitcnt lgkmcnt(0)
; __device__ __forceinline__ float bflo(unsigned w) { return __uint_as_float(w << 16); }
; __device__ __forceinline__ float bfhi(unsigned w) { return __uint_as_float(w & 0xffff0000u); }
; __device__ __forceinline__ unsigned pk2(float lo, float hi) { return pg8::cvt_pk_bf16(lo, hi); }
; __device__ __forceinline__ float silu_f(float v) { return v * __builtin_amdgcn_rcpf(1.f + __expf(-v)); }
; __device__ __forceinline__ void gla_step3(ParamsK p, int l, unsigned char* smem) {
;     ...
; #pragma unroll
;                     for (int db = 0; db < 4; ++db) { const f32x4 n4 = *(const f32x4*)(ngp + db * 16 + fq * 4);
;                         const float r0 = bflo(rgw[db].x), r1 = bfhi(rgw[db].x), r2 = bflo(rgw[db].y), r3 = bfhi(rgw[db].y);
;                         u32x2 w; w.x = pk2(O[db][0] * rstd * n4[0] * silu_f(r0), O[db][1] * rstd * n4[1] * silu_f(r1));
;                         w.y = pk2(O[db][2] * rstd * n4[2] * silu_f(r2), O[db][3] * rstd * n4[3] * silu_f(r3));
;                         *(u32x2*)(MIX + (size_t)row * DM + h * 64 + db * 16 + fq * 4) = w; }
	v_pk_mul_f32 v[176:177], v[216:217], v[176:177]
	s_nop 0
	v_pk_mul_f32 v[176:177], v[178:179], v[176:177]
	v_lshlrev_b32_e32 v178, 16, v103
	v_mul_f32_e32 v139, 0xbfb8aa3b, v178
	v_exp_f32_e32 v139, v139
	v_and_b32_e32 v179, 0xffff0000, v103
	v_pk_mul_f32 v[160:161], v[218:219], v[160:161]
	v_cvt_pk_bf16_f32 v176, v176, v177
	v_add_f32_e32 v139, 1.0, v139
	v_rcp_f32_e32 v216, v139
	v_mul_f32_e32 v139, 0xbfb8aa3b, v179
	v_exp_f32_e32 v139, v139
	s_nop 0
	v_add_f32_e32 v139, 1.0, v139
	v_rcp_f32_e32 v217, v139
	s_nop 0
	v_pk_mul_f32 v[178:179], v[216:217], v[178:179]
	s_nop 0
	v_pk_mul_f32 v[160:161], v[178:179], v[160:161]
	s_nop 0
	v_cvt_pk_bf16_f32 v177, v160, v161
	global_store_dwordx2 v[144:145], v[176:177], off
	ds_read_b128 v[176:179], v237 offset:8256
	v_lshlrev_b32_e32 v160, 16, v100
	v_mul_f32_e32 v139, 0xbfb8aa3b, v160
	v_exp_f32_e32 v139, v139
	v_and_b32_e32 v161, 0xffff0000, v100
	v_add_f32_e32 v139, 1.0, v139
	v_rcp_f32_e32 v216, v139
	v_mul_f32_e32 v139, 0xbfb8aa3b, v161
	v_exp_f32_e32 v139, v139
	s_waitcnt lgkmcnt(0)
	v_pk_mul_f32 v[158:159], v[176:177], v[158:159]
	v_add_f32_e32 v139, 1.0, v139
	v_rcp_f32_e32 v217, v139
	v_pk_mul_f32 v[156:157], v[178:179], v[156:157]
	v_pk_mul_f32 v[160:161], v[216:217], v[160:161]
	s_nop 0
	v_pk_mul_f32 v[158:159], v[160:161], v[158:159]
	v_lshlrev_b32_e32 v160, 16, v101
	v_mul_f32_e32 v139, 0xbfb8aa3b, v160
	v_exp_f32_e32 v139, v139
	v_and_b32_e32 v161, 0xffff0000, v101
	v_cvt_pk_bf16_f32 v158, v158, v159
	v_add_f32_e32 v139, 1.0, v139
	v_rcp_f32_e32 v176, v139
	v_mul_f32_e32 v139, 0xbfb8aa3b, v161
	v_exp_f32_e32 v139, v139
	s_nop 0
	v_add_f32_e32 v139, 1.0, v139
	v_rcp_f32_e32 v177, v139
	s_nop 0
	v_pk_mul_f32 v[160:161], v[176:177], v[160:161]
	s_nop 0
	v_pk_mul_f32 v[156:157], v[160:161], v[156:157]
	v_lshlrev_b32_e32 v160, 16, v98
	v_cvt_pk_bf16_f32 v159, v156, v157
	global_store_dwordx2 v[144:145], v[158:159], off offset:32
	ds_read_b128 v[156:159], v237 offset:8320
	v_mul_f32_e32 v139, 0xbfb8aa3b, v160
	v_exp_f32_e32 v139, v139
	v_and_b32_e32 v161, 0xffff0000, v98
	v_add_f32_e32 v139, 1.0, v139
	v_rcp_f32_e32 v176, v139
	v_mul_f32_e32 v139, 0xbfb8aa3b, v161
	v_exp_f32_e32 v139, v139
	s_waitcnt lgkmcnt(0)
	v_pk_mul_f32 v[154:155], v[156:157], v[154:155]
	v_add_f32_e32 v139, 1.0, v139
	v_rcp_f32_e32 v177, v139
	v_pk_mul_f32 v[152:153], v[158:159], v[152:153]
	v_lshlrev_b32_e32 v158, 16, v104
	v_mul_f32_e32 v143, 0xbfb8aa3b, v158
	v_pk_mul_f32 v[156:157], v[176:177], v[160:161]
	v_exp_f32_e32 v143, v143
	v_pk_mul_f32 v[154:155], v[156:157], v[154:155]
	v_lshlrev_b32_e32 v156, 16, v99
	v_mul_f32_e32 v139, 0xbfb8aa3b, v156
	v_exp_f32_e32 v139, v139
	v_and_b32_e32 v157, 0xffff0000, v99
	v_cvt_pk_bf16_f32 v154, v154, v155
	v_and_b32_e32 v159, 0xffff0000, v104
	v_add_f32_e32 v139, 1.0, v139
	v_rcp_f32_e32 v160, v139
	v_mul_f32_e32 v139, 0xbfb8aa3b, v157
	v_exp_f32_e32 v139, v139
	v_add_f32_e32 v143, 1.0, v143
	v_add_f32_e32 v139, 1.0, v139
	v_rcp_f32_e32 v161, v139
	v_lshlrev_b32_e32 v139, 16, v105
	v_pk_mul_f32 v[156:157], v[160:161], v[156:157]
	s_nop 0
	v_pk_mul_f32 v[152:153], v[156:157], v[152:153]
	v_rcp_f32_e32 v160, v143
	v_cvt_pk_bf16_f32 v155, v152, v153
	global_store_dwordx2 v[144:145], v[154:155], off offset:64
	ds_read_b128 v[152:155], v237 offset:8384
	v_mul_f32_e32 v143, 0xbfb8aa3b, v159
	v_exp_f32_e32 v143, v143
	v_and_b32_e32 v156, 0xffff0000, v105
	v_mul_f32_e32 v157, v147, v148
	v_add_f32_e32 v143, 1.0, v143
	v_rcp_f32_e32 v161, v143
	v_mul_f32_e32 v143, v146, v148
	s_waitcnt lgkmcnt(0)
	v_mul_f32_e32 v146, v154, v143
	v_mul_f32_e32 v143, 0xbfb8aa3b, v139
	v_exp_f32_e32 v143, v143
	v_pk_mul_f32 v[150:151], v[152:153], v[150:151]
	v_pk_mul_f32 v[152:153], v[160:161], v[158:159]
	v_add_f32_e32 v143, 1.0, v143
	v_rcp_f32_e32 v143, v143
	v_pk_mul_f32 v[150:151], v[152:153], v[150:151]
	v_mul_f32_e32 v152, v143, v139
	v_mul_f32_e32 v139, 0xbfb8aa3b, v156
	v_exp_f32_e32 v139, v139
	v_cvt_pk_bf16_f32 v150, v150, v151
	v_add_f32_e32 v139, 1.0, v139
	v_rcp_f32_e32 v154, v139
	s_nop 0
	v_pk_mul_f32 v[148:149], v[154:155], v[156:157]
	s_nop 0
	v_mov_b32_e32 v153, v148
	v_mov_b32_e32 v147, v149
	v_pk_mul_f32 v[146:147], v[152:153], v[146:147]

; __global__ void __launch_bounds__(512, 2) fwd_megakernel(Params p_unused) {
;     extern __shared__ __attribute__((aligned(16))) unsigned char smem[];
;     cg::grid_group grid = cg::this_grid();
;     __shared__ uint4 xb_words;
;     if (threadIdx.x == 0) xb_words = make_uint4(0u, 0u, 0u, 0u);
	.amdhsa_kernel _Z14fwd_megakernel6Params
		.amdhsa_group_segment_fixed_size 28672
		.amdhsa_private_segment_fixed_size 0
		.amdhsa_kernarg_size 456
		.amdhsa_user_sgpr_count 2
		.amdhsa_user_sgpr_dispatch_ptr 0
		.amdhsa_user_sgpr_queue_ptr 0
		.amdhsa_user_sgpr_kernarg_segment_ptr 1
		.amdhsa_user_sgpr_dispatch_id 0
		.amdhsa_user_sgpr_kernarg_preload_length 0
		.amdhsa_user_sgpr_kernarg_preload_offset 0
		.amdhsa_user_sgpr_private_segment_size 0
		.amdhsa_uses_dynamic_stack 0
		.amdhsa_enable_private_segment 0
		.amdhsa_system_sgpr_workgroup_id_x 1
		.amdhsa_system_sgpr_workgroup_id_y 0
		.amdhsa_system_sgpr_workgroup_id_z 0
		.amdhsa_system_sgpr_workgroup_info 0
		.amdhsa_system_vgpr_workitem_id 2
		.amdhsa_next_free_vgpr 256
		.amdhsa_next_free_sgpr 102
		.amdhsa_accum_offset 256
		.amdhsa_reserve_vcc 1
		.amdhsa_float_round_mode_32 0
		.amdhsa_float_round_mode_16_64 0
		.amdhsa_float_denorm_mode_32 3
		.amdhsa_float_denorm_mode_16_64 3
		.amdhsa_dx10_clamp 1
		.amdhsa_ieee_mode 1
		.amdhsa_fp16_overflow 0
		.amdhsa_tg_split 0
		.amdhsa_exception_fp_ieee_invalid_op 0
		.amdhsa_exception_fp_denorm_src 0
		.amdhsa_exception_fp_ieee_div_zero 0
		.amdhsa_exception_fp_ieee_overflow 0
		.amdhsa_exception_fp_ieee_underflow 0
		.amdhsa_exception_fp_ieee_inexact 0
		.amdhsa_exception_int_div_zero 0
	.end_amdhsa_kernel

; __global__ void __launch_bounds__(512, 2) fwd_megakernel(Params p_unused) {
;     extern __shared__ __attribute__((aligned(16))) unsigned char smem[];
;     cg::grid_group grid = cg::this_grid();
;     __shared__ uint4 xb_words;
;     if (threadIdx.x == 0) xb_words = make_uint4(0u, 0u, 0u, 0u);
amdhsa.kernels:
  - .agpr_count:     0
    .args:
      - .offset:         0
        .size:           200
        .value_kind:     by_value
      - .offset:         200
        .size:           4
        .value_kind:     hidden_block_count_x
      - .offset:         204
        .size:           4
        .value_kind:     hidden_block_count_y
      - .offset:         208
        .size:           4
        .value_kind:     hidden_block_count_z
      - .offset:         212
        .size:           2
        .value_kind:     hidden_group_size_x
      - .offset:         214
        .size:           2
        .value_kind:     hidden_group_size_y
      - .offset:         216
        .size:           2
        .value_kind:     hidden_group_size_z
      - .offset:         218
        .size:           2
        .value_kind:     hidden_remainder_x
      - .offset:         220
        .size:           2
        .value_kind:     hidden_remainder_y
      - .offset:         222
        .size:           2
        .value_kind:     hidden_remainder_z
      - .offset:         240
        .size:           8
        .value_kind:     hidden_global_offset_x
      - .offset:         248
        .size:           8
        .value_kind:     hidden_global_offset_y
      - .offset:         256
        .size:           8
        .value_kind:     hidden_global_offset_z
      - .offset:         264
        .size:           2
        .value_kind:     hidden_grid_dims
      - .offset:         288
        .size:           8
        .value_kind:     hidden_multigrid_sync_arg
      - .offset:         320
        .size:           4
        .value_kind:     hidden_dynamic_lds_size
    .group_segment_fixed_size: 28672
    .kernarg_segment_align: 8
    .kernarg_segment_size: 456
    .language:       OpenCL C
    .language_version:
      - 2
      - 0
    .max_flat_workgroup_size: 512
    .name:           _Z14fwd_megakernel6Params
    .private_segment_fixed_size: 0
    .sgpr_count:     108
    .sgpr_spill_count: 178
    .symbol:         _Z14fwd_megakernel6Params.kd
    .uniform_work_group_size: 1
    .uses_dynamic_stack: false
    .vgpr_count:     256
    .vgpr_spill_count: 0
    .wavefront_size: 64
